# A/B: GEMM K-loops with all s_setprio removed
# baseline (speedup 1.0000x reference)
; #define PG8_STAGE(bufoff, gbase, voff) do { _Pragma("unroll") for (int _i = 0; _i < 2; ++_i) \
;         __builtin_amdgcn_global_load_lds((const unsigned*)((const char*)(gbase) + (voff)[_i]), (PG8_LAS unsigned*)(lds + (bufoff) + ldsw + _i * 8192), 16, 0, 0); } while (0)
; #define PG8_LDA(dst, b, h) do { _Pragma("unroll") for (int m = 0; m < 4; ++m) _Pragma("unroll") for (int k = 0; k < 2; ++k) dst[m][k] = *(const PG8_LAS bf16x8*)(lds + PG8_SA(b, h) + aoff + m * 2048 + k * 1024); } while (0)
; #define PG8_MMA(ai, bj, At, Bt) do { __builtin_amdgcn_s_setprio(1); _Pragma("unroll") for (int m = 0; m < 4; ++m) _Pragma("unroll") for (int n = 0; n < 2; ++n) _Pragma("unroll") for (int k = 0; k < 2; ++k) \
;         acc[ai][bj][m][n] = __builtin_amdgcn_mfma_f32_16x16x32_bf16(Bt[n][k], At[m][k], acc[ai][bj][m][n], 0, 0, 0); __builtin_amdgcn_s_setprio(0); } while (0)
; #define PG8_WAIT_V(n) asm volatile("s_waitcnt vmcnt(" #n ")" ::: "memory")
; #define PG8_WAIT_L(n) asm volatile("s_waitcnt lgkmcnt(" #n ")" ::: "memory")
; #define PG8_BAR __builtin_amdgcn_s_barrier()
; #define PG8_SCHED __builtin_amdgcn_sched_barrier(0)
; template <class Epi, class Sched, bool ALIGN_EPI = false, bool SP2 = false>
; __device__ __forceinline__ void gemm_phase(PG8_LAS unsigned char* lds, const Gemm g, const Sched& S, const Epi& E) {
;     ...
;             PG8_WAIT_V(8); PG8_WAIT_L(0); PG8_BAR; PG8_MMA(0, 0, At, B0); PG8_MMA(0, 1, At, B1); PG8_BAR; PG8_SCHED;
;             PG8_LDA(At, 0, 1); PG8_STAGE(PG8_SB(0, 0), b2, voffB); PG8_STAGE(PG8_SB(0, 1), b2 + hstep, voffB); PG8_STAGE(PG8_SA(0, 0), a2, voffA);
;             PG8_WAIT_V(8); PG8_WAIT_L(0); PG8_BAR; PG8_MMA(1, 0, At, B0); PG8_MMA(1, 1, At, B1); PG8_BAR; PG8_SCHED;
.Lodin_noz:
	s_waitcnt vmcnt(8)
	s_waitcnt lgkmcnt(0)
	s_barrier
	s_waitcnt lgkmcnt(0)
	v_mfma_f32_16x16x32_bf16 v[70:73], v[130:133], v[188:191], v[70:73]
	v_mfma_f32_16x16x32_bf16 v[66:69], v[158:161], v[188:191], v[66:69]
	v_mfma_f32_16x16x32_bf16 v[62:65], v[130:133], v[196:199], v[62:65]
	v_mfma_f32_16x16x32_bf16 v[58:61], v[158:161], v[196:199], v[58:61]
	v_mfma_f32_16x16x32_bf16 v[54:57], v[130:133], v[204:207], v[54:57]
	v_mfma_f32_16x16x32_bf16 v[50:53], v[158:161], v[204:207], v[50:53]
	v_mfma_f32_16x16x32_bf16 v[46:49], v[130:133], v[212:215], v[46:49]
	v_mfma_f32_16x16x32_bf16 v[42:45], v[158:161], v[212:215], v[42:45]
	v_mfma_f32_16x16x32_bf16 v[70:73], v[154:157], v[192:195], v[70:73]
	v_mfma_f32_16x16x32_bf16 v[66:69], v[162:165], v[192:195], v[66:69]
	v_mfma_f32_16x16x32_bf16 v[62:65], v[154:157], v[200:203], v[62:65]
	v_mfma_f32_16x16x32_bf16 v[58:61], v[162:165], v[200:203], v[58:61]
	v_mfma_f32_16x16x32_bf16 v[54:57], v[154:157], v[208:211], v[54:57]
	v_mfma_f32_16x16x32_bf16 v[50:53], v[162:165], v[208:211], v[50:53]
	v_mfma_f32_16x16x32_bf16 v[46:49], v[154:157], v[216:219], v[46:49]
	v_mfma_f32_16x16x32_bf16 v[42:45], v[162:165], v[216:219], v[42:45]
	v_mfma_f32_16x16x32_bf16 v[126:129], v[166:169], v[188:191], v[126:129]
	v_mfma_f32_16x16x32_bf16 v[122:125], v[180:183], v[188:191], v[122:125]
	v_mfma_f32_16x16x32_bf16 v[118:121], v[166:169], v[196:199], v[118:121]
	v_mfma_f32_16x16x32_bf16 v[114:117], v[180:183], v[196:199], v[114:117]
	v_mfma_f32_16x16x32_bf16 v[110:113], v[166:169], v[204:207], v[110:113]
	v_mfma_f32_16x16x32_bf16 v[106:109], v[180:183], v[204:207], v[106:109]
	v_mfma_f32_16x16x32_bf16 v[102:105], v[166:169], v[212:215], v[102:105]
	v_mfma_f32_16x16x32_bf16 v[98:101], v[180:183], v[212:215], v[98:101]
	v_mfma_f32_16x16x32_bf16 v[126:129], v[170:173], v[192:195], v[126:129]
	v_mfma_f32_16x16x32_bf16 v[122:125], v[184:187], v[192:195], v[122:125]
	v_mfma_f32_16x16x32_bf16 v[118:121], v[170:173], v[200:203], v[118:121]
	v_mfma_f32_16x16x32_bf16 v[114:117], v[184:187], v[200:203], v[114:117]
	v_mfma_f32_16x16x32_bf16 v[110:113], v[170:173], v[208:211], v[110:113]
	v_mfma_f32_16x16x32_bf16 v[106:109], v[184:187], v[208:211], v[106:109]
	v_mfma_f32_16x16x32_bf16 v[102:105], v[170:173], v[216:219], v[102:105]
	v_mfma_f32_16x16x32_bf16 v[98:101], v[184:187], v[216:219], v[98:101]
	s_barrier
	s_add_i32 s55, s55, s39
	v_lshl_add_u64 v[146:147], s[30:31], 0, v[138:139]
	s_mov_b32 m0, s55
	ds_read_b128 v[188:191], v153 offset:16384
	ds_read_b128 v[192:195], v153 offset:17408
	ds_read_b128 v[196:199], v153 offset:18432
	ds_read_b128 v[200:203], v153 offset:19456
	ds_read_b128 v[204:207], v153 offset:20480
	ds_read_b128 v[208:211], v153 offset:21504
	ds_read_b128 v[212:215], v153 offset:22528
	ds_read_b128 v[216:219], v153 offset:23552
	global_load_lds_dwordx4 v[146:147], off
	s_add_i32 m0, s55, 0x2000
	s_add_u32 s56, s30, 0x40000
	v_lshl_add_u64 v[220:221], s[30:31], 0, v[134:135]
	s_addc_u32 s57, s31, 0
	s_add_i32 s55, s58, s39
	global_load_lds_dwordx4 v[220:221], off
	v_lshl_add_u64 v[222:223], s[56:57], 0, v[138:139]
	s_mov_b32 m0, s55
	v_lshl_add_u64 v[228:229], s[34:35], 0, v[136:137]
	global_load_lds_dwordx4 v[222:223], off
	v_lshl_add_u64 v[222:223], s[56:57], 0, v[134:135]
	s_add_i32 m0, s55, 0x2000
	s_nop 0
	global_load_lds_dwordx4 v[222:223], off
	v_lshl_add_u64 v[222:223], s[34:35], 0, v[140:141]
	s_mov_b32 m0, s40
	s_nop 0
	global_load_lds_dwordx4 v[222:223], off
	s_mov_b32 m0, s41
	s_nop 0
	global_load_lds_dwordx4 v[228:229], off
	s_waitcnt vmcnt(8)
	s_waitcnt lgkmcnt(0)
	s_barrier
	s_waitcnt lgkmcnt(0)
	v_mfma_f32_16x16x32_bf16 v[30:33], v[130:133], v[188:191], v[30:33]
	v_mfma_f32_16x16x32_bf16 v[26:29], v[158:161], v[188:191], v[26:29]
	v_mfma_f32_16x16x32_bf16 v[22:25], v[130:133], v[196:199], v[22:25]
	v_mfma_f32_16x16x32_bf16 v[18:21], v[158:161], v[196:199], v[18:21]
	v_mfma_f32_16x16x32_bf16 v[14:17], v[130:133], v[204:207], v[14:17]
	v_mfma_f32_16x16x32_bf16 v[10:13], v[158:161], v[204:207], v[10:13]
	v_mfma_f32_16x16x32_bf16 v[6:9], v[130:133], v[212:215], v[6:9]
	v_mfma_f32_16x16x32_bf16 v[2:5], v[158:161], v[212:215], v[2:5]
	v_mfma_f32_16x16x32_bf16 v[30:33], v[154:157], v[192:195], v[30:33]
	v_mfma_f32_16x16x32_bf16 v[26:29], v[162:165], v[192:195], v[26:29]
	v_mfma_f32_16x16x32_bf16 v[22:25], v[154:157], v[200:203], v[22:25]
	v_mfma_f32_16x16x32_bf16 v[18:21], v[162:165], v[200:203], v[18:21]
	v_mfma_f32_16x16x32_bf16 v[14:17], v[154:157], v[208:211], v[14:17]
	v_mfma_f32_16x16x32_bf16 v[10:13], v[162:165], v[208:211], v[10:13]
	v_mfma_f32_16x16x32_bf16 v[6:9], v[154:157], v[216:219], v[6:9]
	v_mfma_f32_16x16x32_bf16 v[2:5], v[162:165], v[216:219], v[2:5]
	v_mfma_f32_16x16x32_bf16 v[94:97], v[166:169], v[188:191], v[94:97]
	v_mfma_f32_16x16x32_bf16 v[90:93], v[180:183], v[188:191], v[90:93]
	v_mfma_f32_16x16x32_bf16 v[86:89], v[166:169], v[196:199], v[86:89]
	v_mfma_f32_16x16x32_bf16 v[82:85], v[180:183], v[196:199], v[82:85]
	v_mfma_f32_16x16x32_bf16 v[78:81], v[166:169], v[204:207], v[78:81]
	v_mfma_f32_16x16x32_bf16 v[74:77], v[180:183], v[204:207], v[74:77]
	v_mfma_f32_16x16x32_bf16 v[38:41], v[166:169], v[212:215], v[38:41]
	v_mfma_f32_16x16x32_bf16 v[34:37], v[180:183], v[212:215], v[34:37]
	v_mfma_f32_16x16x32_bf16 v[94:97], v[170:173], v[192:195], v[94:97]
	v_mfma_f32_16x16x32_bf16 v[90:93], v[184:187], v[192:195], v[90:93]
	v_mfma_f32_16x16x32_bf16 v[86:89], v[170:173], v[200:203], v[86:89]
	v_mfma_f32_16x16x32_bf16 v[82:85], v[184:187], v[200:203], v[82:85]
	v_mfma_f32_16x16x32_bf16 v[78:81], v[170:173], v[208:211], v[78:81]
	v_mfma_f32_16x16x32_bf16 v[74:77], v[184:187], v[208:211], v[74:77]
	v_mfma_f32_16x16x32_bf16 v[38:41], v[170:173], v[216:219], v[38:41]
	v_mfma_f32_16x16x32_bf16 v[34:37], v[184:187], v[216:219], v[34:37]
	s_barrier
; #define PG8_STAGE(bufoff, gbase, voff) do { _Pragma("unroll") for (int _i = 0; _i < 2; ++_i) \
;         __builtin_amdgcn_global_load_lds((const unsigned*)((const char*)(gbase) + (voff)[_i]), (PG8_LAS unsigned*)(lds + (bufoff) + ldsw + _i * 8192), 16, 0, 0); } while (0)
; #define PG8_LDA(dst, b, h) do { _Pragma("unroll") for (int m = 0; m < 4; ++m) _Pragma("unroll") for (int k = 0; k < 2; ++k) dst[m][k] = *(const PG8_LAS bf16x8*)(lds + PG8_SA(b, h) + aoff + m * 2048 + k * 1024); } while (0)
; #define PG8_LDB(dst, b, h) do { _Pragma("unroll") for (int n = 0; n < 2; ++n) _Pragma("unroll") for (int k = 0; k < 2; ++k) dst[n][k] = *(const PG8_LAS bf16x8*)(lds + PG8_SB(b, h) + boff + n * 2048 + k * 1024); } while (0)
; #define PG8_MMA(ai, bj, At, Bt) do { __builtin_amdgcn_s_setprio(1); _Pragma("unroll") for (int m = 0; m < 4; ++m) _Pragma("unroll") for (int n = 0; n < 2; ++n) _Pragma("unroll") for (int k = 0; k < 2; ++k) \
;         acc[ai][bj][m][n] = __builtin_amdgcn_mfma_f32_16x16x32_bf16(Bt[n][k], At[m][k], acc[ai][bj][m][n], 0, 0, 0); __builtin_amdgcn_s_setprio(0); } while (0)
; #define PG8_WAIT_V(n) asm volatile("s_waitcnt vmcnt(" #n ")" ::: "memory")
; #define PG8_WAIT_L(n) asm volatile("s_waitcnt lgkmcnt(" #n ")" ::: "memory")
; #define PG8_BAR __builtin_amdgcn_s_barrier()
; #define PG8_SCHED __builtin_amdgcn_sched_barrier(0)
; template <class Epi, class Sched, bool ALIGN_EPI = false, bool SP2 = false>
; __device__ __forceinline__ void gemm_phase(PG8_LAS unsigned char* lds, const Gemm g, const Sched& S, const Epi& E) {
;     ...
;             PG8_LDB(B0, 1, 0); PG8_LDB(B1, 1, 1); PG8_SCHED; PG8_LDA(At, 1, 0); PG8_STAGE(PG8_SA(0, 1), a2 + hstep, voffA);
;             PG8_WAIT_V(8); PG8_WAIT_L(0); PG8_BAR; PG8_MMA(0, 0, At, B0); PG8_MMA(0, 1, At, B1); PG8_BAR; PG8_SCHED;
	s_add_i32 s55, 0, 0x18000
	v_add_u32_e32 v148, s55, v151
	s_add_i32 s56, 0, 0x1c000
	ds_read_b128 v[130:133], v148
	ds_read_b128 v[154:157], v148 offset:1024
	ds_read_b128 v[158:161], v148 offset:2048
	ds_read_b128 v[162:165], v148 offset:3072
	v_add_u32_e32 v148, s56, v151
	ds_read_b128 v[166:169], v148
	ds_read_b128 v[170:173], v148 offset:1024
	ds_read_b128 v[180:183], v148 offset:2048
	ds_read_b128 v[184:187], v148 offset:3072
	s_add_u32 s34, s34, 0x40000
	s_addc_u32 s35, s35, 0
	s_mov_b32 m0, s42
	v_lshl_add_u64 v[230:231], s[34:35], 0, v[140:141]
	ds_read_b128 v[188:191], v153 offset:32768
	ds_read_b128 v[192:195], v153 offset:33792
	ds_read_b128 v[196:199], v153 offset:34816
	ds_read_b128 v[200:203], v153 offset:35840
	ds_read_b128 v[204:207], v153 offset:36864
	ds_read_b128 v[208:211], v153 offset:37888
	ds_read_b128 v[212:215], v153 offset:38912
	ds_read_b128 v[216:219], v153 offset:39936
	global_load_lds_dwordx4 v[230:231], off
	v_lshl_add_u64 v[230:231], s[34:35], 0, v[136:137]
	s_mov_b32 m0, s43
	s_nop 0
	global_load_lds_dwordx4 v[230:231], off
	s_waitcnt vmcnt(8)
	s_waitcnt lgkmcnt(0)
	s_barrier
	s_waitcnt lgkmcnt(0)
	v_mfma_f32_16x16x32_bf16 v[70:73], v[130:133], v[188:191], v[70:73]
	v_mfma_f32_16x16x32_bf16 v[66:69], v[158:161], v[188:191], v[66:69]
	v_mfma_f32_16x16x32_bf16 v[62:65], v[130:133], v[196:199], v[62:65]
	v_mfma_f32_16x16x32_bf16 v[58:61], v[158:161], v[196:199], v[58:61]
	v_mfma_f32_16x16x32_bf16 v[54:57], v[130:133], v[204:207], v[54:57]
	v_mfma_f32_16x16x32_bf16 v[50:53], v[158:161], v[204:207], v[50:53]
	v_mfma_f32_16x16x32_bf16 v[46:49], v[130:133], v[212:215], v[46:49]
	v_mfma_f32_16x16x32_bf16 v[42:45], v[158:161], v[212:215], v[42:45]
	v_mfma_f32_16x16x32_bf16 v[70:73], v[154:157], v[192:195], v[70:73]
	v_mfma_f32_16x16x32_bf16 v[66:69], v[162:165], v[192:195], v[66:69]
	v_mfma_f32_16x16x32_bf16 v[62:65], v[154:157], v[200:203], v[62:65]
	v_mfma_f32_16x16x32_bf16 v[58:61], v[162:165], v[200:203], v[58:61]
	v_mfma_f32_16x16x32_bf16 v[54:57], v[154:157], v[208:211], v[54:57]
	v_mfma_f32_16x16x32_bf16 v[50:53], v[162:165], v[208:211], v[50:53]
	v_mfma_f32_16x16x32_bf16 v[46:49], v[154:157], v[216:219], v[46:49]
	v_mfma_f32_16x16x32_bf16 v[42:45], v[162:165], v[216:219], v[42:45]
	v_mfma_f32_16x16x32_bf16 v[126:129], v[166:169], v[188:191], v[126:129]
	v_mfma_f32_16x16x32_bf16 v[122:125], v[180:183], v[188:191], v[122:125]
	v_mfma_f32_16x16x32_bf16 v[118:121], v[166:169], v[196:199], v[118:121]
	v_mfma_f32_16x16x32_bf16 v[114:117], v[180:183], v[196:199], v[114:117]
	v_mfma_f32_16x16x32_bf16 v[110:113], v[166:169], v[204:207], v[110:113]
	v_mfma_f32_16x16x32_bf16 v[106:109], v[180:183], v[204:207], v[106:109]
	v_mfma_f32_16x16x32_bf16 v[102:105], v[166:169], v[212:215], v[102:105]
	v_mfma_f32_16x16x32_bf16 v[98:101], v[180:183], v[212:215], v[98:101]
	v_mfma_f32_16x16x32_bf16 v[126:129], v[170:173], v[192:195], v[126:129]
	v_mfma_f32_16x16x32_bf16 v[122:125], v[184:187], v[192:195], v[122:125]
	v_mfma_f32_16x16x32_bf16 v[118:121], v[170:173], v[200:203], v[118:121]
	v_mfma_f32_16x16x32_bf16 v[114:117], v[184:187], v[200:203], v[114:117]
	v_mfma_f32_16x16x32_bf16 v[110:113], v[170:173], v[208:211], v[110:113]
	v_mfma_f32_16x16x32_bf16 v[106:109], v[184:187], v[208:211], v[106:109]
	v_mfma_f32_16x16x32_bf16 v[102:105], v[170:173], v[216:219], v[102:105]
	v_mfma_f32_16x16x32_bf16 v[98:101], v[184:187], v[216:219], v[98:101]
	s_barrier
; #define PG8_STAGE(bufoff, gbase, voff) do { _Pragma("unroll") for (int _i = 0; _i < 2; ++_i) \
;         __builtin_amdgcn_global_load_lds((const unsigned*)((const char*)(gbase) + (voff)[_i]), (PG8_LAS unsigned*)(lds + (bufoff) + ldsw + _i * 8192), 16, 0, 0); } while (0)
; #define PG8_LDA(dst, b, h) do { _Pragma("unroll") for (int m = 0; m < 4; ++m) _Pragma("unroll") for (int k = 0; k < 2; ++k) dst[m][k] = *(const PG8_LAS bf16x8*)(lds + PG8_SA(b, h) + aoff + m * 2048 + k * 1024); } while (0)
; #define PG8_MMA(ai, bj, At, Bt) do { __builtin_amdgcn_s_setprio(1); _Pragma("unroll") for (int m = 0; m < 4; ++m) _Pragma("unroll") for (int n = 0; n < 2; ++n) _Pragma("unroll") for (int k = 0; k < 2; ++k) \
;         acc[ai][bj][m][n] = __builtin_amdgcn_mfma_f32_16x16x32_bf16(Bt[n][k], At[m][k], acc[ai][bj][m][n], 0, 0, 0); __builtin_amdgcn_s_setprio(0); } while (0)
; #define PG8_WAIT_V(n) asm volatile("s_waitcnt vmcnt(" #n ")" ::: "memory")
; #define PG8_WAIT_L(n) asm volatile("s_waitcnt lgkmcnt(" #n ")" ::: "memory")
; #define PG8_BAR __builtin_amdgcn_s_barrier()
; #define PG8_SCHED __builtin_amdgcn_sched_barrier(0)
; template <class Epi, class Sched, bool ALIGN_EPI = false, bool SP2 = false>
; __device__ __forceinline__ void gemm_phase(PG8_LAS unsigned char* lds, const Gemm g, const Sched& S, const Epi& E) {
;     ...
;         for (int t = 0; t < nt; t += 2) {
;             const bool last = (t == nt - 2);
;             const char* a1 = cA + (size_t)(t + 1) * kstep;
;             const char* a2 = last ? nA : cA + (size_t)(t + 2) * kstep; const char* b2 = last ? nB : cB + (size_t)(t + 2) * kstep;
;             const char* a3 = a2 + kstep; const char* b3 = b2 + kstep;
;     ...
;             PG8_LDA(At, 1, 1); PG8_STAGE(PG8_SB(1, 0), b3, voffB); PG8_STAGE(PG8_SB(1, 1), b3 + hstep, voffB); PG8_STAGE(PG8_SA(1, 0), a3, voffA);
;             PG8_WAIT_V(8); PG8_WAIT_L(0); PG8_BAR; PG8_MMA(1, 0, At, B0); PG8_MMA(1, 1, At, B1); PG8_BAR; PG8_SCHED;
	s_add_i32 s34, s55, s39
	v_lshl_add_u64 v[146:147], v[146:147], 0, s[96:97]
	s_mov_b32 m0, s34
	ds_read_b128 v[188:191], v153 offset:49152
	ds_read_b128 v[192:195], v153 offset:50176
	ds_read_b128 v[196:199], v153 offset:51200
	ds_read_b128 v[200:203], v153 offset:52224
	ds_read_b128 v[204:207], v153 offset:53248
	ds_read_b128 v[208:211], v153 offset:54272
	ds_read_b128 v[212:215], v153 offset:55296
	ds_read_b128 v[216:219], v153 offset:56320
	global_load_lds_dwordx4 v[146:147], off
	s_add_i32 m0, s34, 0x2000
	s_add_u32 s30, s30, 0x40080
	v_lshl_add_u64 v[146:147], v[220:221], 0, s[96:97]
	s_addc_u32 s31, s31, 0
	s_add_i32 s34, s56, s39
	global_load_lds_dwordx4 v[146:147], off
	v_lshl_add_u64 v[146:147], s[30:31], 0, v[138:139]
	s_mov_b32 m0, s34
	s_nop 0
	global_load_lds_dwordx4 v[146:147], off
	v_lshl_add_u64 v[146:147], s[30:31], 0, v[134:135]
	s_add_i32 m0, s34, 0x2000
	s_nop 0
	global_load_lds_dwordx4 v[146:147], off
	v_lshl_add_u64 v[146:147], v[222:223], 0, s[96:97]
	s_mov_b32 m0, s48
	s_nop 0
	global_load_lds_dwordx4 v[146:147], off
	v_lshl_add_u64 v[146:147], v[228:229], 0, s[96:97]
	s_mov_b32 m0, s49
	s_nop 0
	global_load_lds_dwordx4 v[146:147], off
	s_waitcnt vmcnt(8)
	s_waitcnt lgkmcnt(0)
	s_barrier
	s_waitcnt lgkmcnt(0)
	v_mfma_f32_16x16x32_bf16 v[30:33], v[130:133], v[188:191], v[30:33]
	v_mfma_f32_16x16x32_bf16 v[26:29], v[158:161], v[188:191], v[26:29]
	v_mfma_f32_16x16x32_bf16 v[22:25], v[130:133], v[196:199], v[22:25]
	v_mfma_f32_16x16x32_bf16 v[18:21], v[158:161], v[196:199], v[18:21]
	v_mfma_f32_16x16x32_bf16 v[14:17], v[130:133], v[204:207], v[14:17]
	v_mfma_f32_16x16x32_bf16 v[10:13], v[158:161], v[204:207], v[10:13]
	v_mfma_f32_16x16x32_bf16 v[6:9], v[130:133], v[212:215], v[6:9]
	v_mfma_f32_16x16x32_bf16 v[2:5], v[158:161], v[212:215], v[2:5]
	v_mfma_f32_16x16x32_bf16 v[30:33], v[154:157], v[192:195], v[30:33]
	v_mfma_f32_16x16x32_bf16 v[26:29], v[162:165], v[192:195], v[26:29]
	v_mfma_f32_16x16x32_bf16 v[22:25], v[154:157], v[200:203], v[22:25]
	v_mfma_f32_16x16x32_bf16 v[18:21], v[162:165], v[200:203], v[18:21]
	v_mfma_f32_16x16x32_bf16 v[14:17], v[154:157], v[208:211], v[14:17]
	v_mfma_f32_16x16x32_bf16 v[10:13], v[162:165], v[208:211], v[10:13]
	v_mfma_f32_16x16x32_bf16 v[6:9], v[154:157], v[216:219], v[6:9]
	v_mfma_f32_16x16x32_bf16 v[2:5], v[162:165], v[216:219], v[2:5]
	v_mfma_f32_16x16x32_bf16 v[94:97], v[166:169], v[188:191], v[94:97]
	v_mfma_f32_16x16x32_bf16 v[90:93], v[180:183], v[188:191], v[90:93]
	v_mfma_f32_16x16x32_bf16 v[86:89], v[166:169], v[196:199], v[86:89]
	v_mfma_f32_16x16x32_bf16 v[82:85], v[180:183], v[196:199], v[82:85]
	v_mfma_f32_16x16x32_bf16 v[78:81], v[166:169], v[204:207], v[78:81]
	v_mfma_f32_16x16x32_bf16 v[74:77], v[180:183], v[204:207], v[74:77]
	v_mfma_f32_16x16x32_bf16 v[38:41], v[166:169], v[212:215], v[38:41]
	v_mfma_f32_16x16x32_bf16 v[34:37], v[180:183], v[212:215], v[34:37]
	v_mfma_f32_16x16x32_bf16 v[94:97], v[170:173], v[192:195], v[94:97]
	v_mfma_f32_16x16x32_bf16 v[90:93], v[184:187], v[192:195], v[90:93]
	v_mfma_f32_16x16x32_bf16 v[86:89], v[170:173], v[200:203], v[86:89]
	v_mfma_f32_16x16x32_bf16 v[82:85], v[184:187], v[200:203], v[82:85]
	v_mfma_f32_16x16x32_bf16 v[78:81], v[170:173], v[208:211], v[78:81]
	v_mfma_f32_16x16x32_bf16 v[74:77], v[184:187], v[208:211], v[74:77]
	v_mfma_f32_16x16x32_bf16 v[38:41], v[170:173], v[216:219], v[38:41]
	v_mfma_f32_16x16x32_bf16 v[34:37], v[184:187], v[216:219], v[34:37]
	s_barrier
	s_add_i32 s54, s54, 2
	s_add_u32 s28, s28, 0x100
	s_addc_u32 s29, s29, 0
	s_add_u32 s52, s52, 0x100
	s_addc_u32 s53, s53, 0
	s_cmp_gt_u32 s54, 13
	s_cbranch_scc0 .LBB0_185
	s_and_b64 vcc, exec, s[16:17]
	s_cbranch_vccz .LBB0_188
	s_barrier

; #define PG8_STAGE(bufoff, gbase, voff) do { _Pragma("unroll") for (int _i = 0; _i < 2; ++_i) \
;         __builtin_amdgcn_global_load_lds((const unsigned*)((const char*)(gbase) + (voff)[_i]), (PG8_LAS unsigned*)(lds + (bufoff) + ldsw + _i * 8192), 16, 0, 0); } while (0)
; #define PG8_LDA(dst, b, h) do { _Pragma("unroll") for (int m = 0; m < 4; ++m) _Pragma("unroll") for (int k = 0; k < 2; ++k) dst[m][k] = *(const PG8_LAS bf16x8*)(lds + PG8_SA(b, h) + aoff + m * 2048 + k * 1024); } while (0)
; #define PG8_MMA(ai, bj, At, Bt) do { __builtin_amdgcn_s_setprio(1); _Pragma("unroll") for (int m = 0; m < 4; ++m) _Pragma("unroll") for (int n = 0; n < 2; ++n) _Pragma("unroll") for (int k = 0; k < 2; ++k) \
;         acc[ai][bj][m][n] = __builtin_amdgcn_mfma_f32_16x16x32_bf16(Bt[n][k], At[m][k], acc[ai][bj][m][n], 0, 0, 0); __builtin_amdgcn_s_setprio(0); } while (0)
; #define PG8_WAIT_V(n) asm volatile("s_waitcnt vmcnt(" #n ")" ::: "memory")
; #define PG8_WAIT_L(n) asm volatile("s_waitcnt lgkmcnt(" #n ")" ::: "memory")
; #define PG8_BAR __builtin_amdgcn_s_barrier()
; #define PG8_SCHED __builtin_amdgcn_sched_barrier(0)
; template <class Epi, class Sched, bool ALIGN_EPI = false, bool SP2 = false>
; __device__ __forceinline__ void gemm_phase(PG8_LAS unsigned char* lds, const Gemm g, const Sched& S, const Epi& E) {
;     ...
;             PG8_WAIT_V(8); PG8_WAIT_L(0); PG8_BAR; PG8_MMA(0, 0, At, B0); PG8_MMA(0, 1, At, B1); PG8_BAR; PG8_SCHED;
;             PG8_LDA(At, 0, 1); PG8_STAGE(PG8_SB(0, 0), b2, voffB); PG8_STAGE(PG8_SB(0, 1), b2 + hstep, voffB); PG8_STAGE(PG8_SA(0, 0), a2, voffA);
;             PG8_WAIT_V(8); PG8_WAIT_L(0); PG8_BAR; PG8_MMA(1, 0, At, B0); PG8_MMA(1, 1, At, B1); PG8_BAR; PG8_SCHED;
.Lodout_noz:
	s_waitcnt vmcnt(8)
	s_waitcnt lgkmcnt(0)
	s_barrier
	s_waitcnt lgkmcnt(0)
	v_mfma_f32_16x16x32_bf16 v[158:161], v[66:69], v[162:165], v[158:161]
	v_mfma_f32_16x16x32_bf16 v[154:157], v[82:85], v[162:165], v[154:157]
	v_mfma_f32_16x16x32_bf16 v[142:145], v[66:69], v[188:191], v[142:145]
	v_mfma_f32_16x16x32_bf16 v[138:141], v[82:85], v[188:191], v[138:141]
	v_mfma_f32_16x16x32_bf16 v[114:117], v[66:69], v[196:199], v[114:117]
	v_mfma_f32_16x16x32_bf16 v[110:113], v[82:85], v[196:199], v[110:113]
	v_mfma_f32_16x16x32_bf16 v[90:93], v[66:69], v[210:213], v[90:93]
	v_mfma_f32_16x16x32_bf16 v[86:89], v[82:85], v[210:213], v[86:89]
	v_mfma_f32_16x16x32_bf16 v[158:161], v[70:73], v[166:169], v[158:161]
	v_mfma_f32_16x16x32_bf16 v[154:157], v[94:97], v[166:169], v[154:157]
	v_mfma_f32_16x16x32_bf16 v[142:145], v[70:73], v[192:195], v[142:145]
	v_mfma_f32_16x16x32_bf16 v[138:141], v[94:97], v[192:195], v[138:141]
	v_mfma_f32_16x16x32_bf16 v[114:117], v[70:73], v[206:209], v[114:117]
	v_mfma_f32_16x16x32_bf16 v[110:113], v[94:97], v[206:209], v[110:113]
	v_mfma_f32_16x16x32_bf16 v[90:93], v[70:73], v[214:217], v[90:93]
	v_mfma_f32_16x16x32_bf16 v[86:89], v[94:97], v[214:217], v[86:89]
	v_mfma_f32_16x16x32_bf16 v[150:153], v[106:109], v[162:165], v[150:153]
	v_mfma_f32_16x16x32_bf16 v[146:149], v[130:133], v[162:165], v[146:149]
	v_mfma_f32_16x16x32_bf16 v[126:129], v[106:109], v[188:191], v[126:129]
	v_mfma_f32_16x16x32_bf16 v[122:125], v[130:133], v[188:191], v[122:125]
	v_mfma_f32_16x16x32_bf16 v[102:105], v[106:109], v[196:199], v[102:105]
	v_mfma_f32_16x16x32_bf16 v[98:101], v[130:133], v[196:199], v[98:101]
	v_mfma_f32_16x16x32_bf16 v[78:81], v[106:109], v[210:213], v[78:81]
	v_mfma_f32_16x16x32_bf16 v[74:77], v[130:133], v[210:213], v[74:77]
	v_mfma_f32_16x16x32_bf16 v[150:153], v[118:121], v[166:169], v[150:153]
	v_mfma_f32_16x16x32_bf16 v[146:149], v[134:137], v[166:169], v[146:149]
	v_mfma_f32_16x16x32_bf16 v[126:129], v[118:121], v[192:195], v[126:129]
	v_mfma_f32_16x16x32_bf16 v[122:125], v[134:137], v[192:195], v[122:125]
	v_mfma_f32_16x16x32_bf16 v[102:105], v[118:121], v[206:209], v[102:105]
	v_mfma_f32_16x16x32_bf16 v[98:101], v[134:137], v[206:209], v[98:101]
	v_mfma_f32_16x16x32_bf16 v[78:81], v[118:121], v[214:217], v[78:81]
	v_mfma_f32_16x16x32_bf16 v[74:77], v[134:137], v[214:217], v[74:77]
	s_barrier
	s_add_i32 s56, s56, s42
	v_lshl_add_u64 v[200:201], s[12:13], 0, v[180:181]
	s_mov_b32 m0, s56
	ds_read_b128 v[162:165], v204 offset:16384
	ds_read_b128 v[166:169], v204 offset:17408
	ds_read_b128 v[188:191], v204 offset:18432
	ds_read_b128 v[192:195], v204 offset:19456
	ds_read_b128 v[196:199], v204 offset:20480
	ds_read_b128 v[206:209], v204 offset:21504
	ds_read_b128 v[210:213], v204 offset:22528
	ds_read_b128 v[214:217], v204 offset:23552
	global_load_lds_dwordx4 v[200:201], off
	s_add_i32 m0, s56, 0x2000
	s_add_u32 s56, s12, 0x40000
	v_lshl_add_u64 v[218:219], s[12:13], 0, v[170:171]
	s_addc_u32 s57, s13, 0
	s_add_i32 s58, s58, s42
	global_load_lds_dwordx4 v[218:219], off
	v_lshl_add_u64 v[220:221], s[56:57], 0, v[180:181]
	s_mov_b32 m0, s58
	v_lshl_add_u64 v[222:223], s[36:37], 0, v[172:173]
	global_load_lds_dwordx4 v[220:221], off
	v_lshl_add_u64 v[220:221], s[56:57], 0, v[170:171]
	s_add_i32 m0, s58, 0x2000
	s_nop 0
	global_load_lds_dwordx4 v[220:221], off
	v_lshl_add_u64 v[220:221], s[36:37], 0, v[182:183]
	s_mov_b32 m0, s43
	s_nop 0
	global_load_lds_dwordx4 v[220:221], off
	s_mov_b32 m0, s44
	s_nop 0
	global_load_lds_dwordx4 v[222:223], off
	s_waitcnt vmcnt(8)
	s_waitcnt lgkmcnt(0)
	s_barrier
	s_waitcnt lgkmcnt(0)
	v_mfma_f32_16x16x32_bf16 v[62:65], v[66:69], v[162:165], v[62:65]
	v_mfma_f32_16x16x32_bf16 v[58:61], v[82:85], v[162:165], v[58:61]
	v_mfma_f32_16x16x32_bf16 v[46:49], v[66:69], v[188:191], v[46:49]
	v_mfma_f32_16x16x32_bf16 v[42:45], v[82:85], v[188:191], v[42:45]
	v_mfma_f32_16x16x32_bf16 v[30:33], v[66:69], v[196:199], v[30:33]
	v_mfma_f32_16x16x32_bf16 v[26:29], v[82:85], v[196:199], v[26:29]
	v_mfma_f32_16x16x32_bf16 v[14:17], v[66:69], v[210:213], v[14:17]
	v_mfma_f32_16x16x32_bf16 v[10:13], v[82:85], v[210:213], v[10:13]
	v_mfma_f32_16x16x32_bf16 v[62:65], v[70:73], v[166:169], v[62:65]
	v_mfma_f32_16x16x32_bf16 v[58:61], v[94:97], v[166:169], v[58:61]
	v_mfma_f32_16x16x32_bf16 v[46:49], v[70:73], v[192:195], v[46:49]
	v_mfma_f32_16x16x32_bf16 v[42:45], v[94:97], v[192:195], v[42:45]
	v_mfma_f32_16x16x32_bf16 v[30:33], v[70:73], v[206:209], v[30:33]
	v_mfma_f32_16x16x32_bf16 v[26:29], v[94:97], v[206:209], v[26:29]
	v_mfma_f32_16x16x32_bf16 v[14:17], v[70:73], v[214:217], v[14:17]
	v_mfma_f32_16x16x32_bf16 v[10:13], v[94:97], v[214:217], v[10:13]
	v_mfma_f32_16x16x32_bf16 v[54:57], v[106:109], v[162:165], v[54:57]
	v_mfma_f32_16x16x32_bf16 v[50:53], v[130:133], v[162:165], v[50:53]
	v_mfma_f32_16x16x32_bf16 v[38:41], v[106:109], v[188:191], v[38:41]
	v_mfma_f32_16x16x32_bf16 v[34:37], v[130:133], v[188:191], v[34:37]
	v_mfma_f32_16x16x32_bf16 v[22:25], v[106:109], v[196:199], v[22:25]
	v_mfma_f32_16x16x32_bf16 v[18:21], v[130:133], v[196:199], v[18:21]
	v_mfma_f32_16x16x32_bf16 v[6:9], v[106:109], v[210:213], v[6:9]
	v_mfma_f32_16x16x32_bf16 v[2:5], v[130:133], v[210:213], v[2:5]
	v_mfma_f32_16x16x32_bf16 v[54:57], v[118:121], v[166:169], v[54:57]
	v_mfma_f32_16x16x32_bf16 v[50:53], v[134:137], v[166:169], v[50:53]
	v_mfma_f32_16x16x32_bf16 v[38:41], v[118:121], v[192:195], v[38:41]
	v_mfma_f32_16x16x32_bf16 v[34:37], v[134:137], v[192:195], v[34:37]
	v_mfma_f32_16x16x32_bf16 v[22:25], v[118:121], v[206:209], v[22:25]
	v_mfma_f32_16x16x32_bf16 v[18:21], v[134:137], v[206:209], v[18:21]
	v_mfma_f32_16x16x32_bf16 v[6:9], v[118:121], v[214:217], v[6:9]
	v_mfma_f32_16x16x32_bf16 v[2:5], v[134:137], v[214:217], v[2:5]
	s_barrier
; #define PG8_STAGE(bufoff, gbase, voff) do { _Pragma("unroll") for (int _i = 0; _i < 2; ++_i) \
;         __builtin_amdgcn_global_load_lds((const unsigned*)((const char*)(gbase) + (voff)[_i]), (PG8_LAS unsigned*)(lds + (bufoff) + ldsw + _i * 8192), 16, 0, 0); } while (0)
; #define PG8_LDA(dst, b, h) do { _Pragma("unroll") for (int m = 0; m < 4; ++m) _Pragma("unroll") for (int k = 0; k < 2; ++k) dst[m][k] = *(const PG8_LAS bf16x8*)(lds + PG8_SA(b, h) + aoff + m * 2048 + k * 1024); } while (0)
; #define PG8_LDB(dst, b, h) do { _Pragma("unroll") for (int n = 0; n < 2; ++n) _Pragma("unroll") for (int k = 0; k < 2; ++k) dst[n][k] = *(const PG8_LAS bf16x8*)(lds + PG8_SB(b, h) + boff + n * 2048 + k * 1024); } while (0)
; #define PG8_MMA(ai, bj, At, Bt) do { __builtin_amdgcn_s_setprio(1); _Pragma("unroll") for (int m = 0; m < 4; ++m) _Pragma("unroll") for (int n = 0; n < 2; ++n) _Pragma("unroll") for (int k = 0; k < 2; ++k) \
;         acc[ai][bj][m][n] = __builtin_amdgcn_mfma_f32_16x16x32_bf16(Bt[n][k], At[m][k], acc[ai][bj][m][n], 0, 0, 0); __builtin_amdgcn_s_setprio(0); } while (0)
; #define PG8_WAIT_V(n) asm volatile("s_waitcnt vmcnt(" #n ")" ::: "memory")
; #define PG8_WAIT_L(n) asm volatile("s_waitcnt lgkmcnt(" #n ")" ::: "memory")
; #define PG8_BAR __builtin_amdgcn_s_barrier()
; #define PG8_SCHED __builtin_amdgcn_sched_barrier(0)
; template <class Epi, class Sched, bool ALIGN_EPI = false, bool SP2 = false>
; __device__ __forceinline__ void gemm_phase(PG8_LAS unsigned char* lds, const Gemm g, const Sched& S, const Epi& E) {
;     ...
;             PG8_LDB(B0, 1, 0); PG8_LDB(B1, 1, 1); PG8_SCHED; PG8_LDA(At, 1, 0); PG8_STAGE(PG8_SA(0, 1), a2 + hstep, voffA);
;             PG8_WAIT_V(8); PG8_WAIT_L(0); PG8_BAR; PG8_MMA(0, 0, At, B0); PG8_MMA(0, 1, At, B1); PG8_BAR; PG8_SCHED;
	s_add_i32 s56, 0, 0x18000
	s_add_i32 s57, 0, 0x1c000
	v_add_u32_e32 v94, s56, v203
	v_add_u32_e32 v134, s57, v203
	ds_read_b128 v[66:69], v94
	ds_read_b128 v[70:73], v94 offset:1024
	ds_read_b128 v[82:85], v94 offset:2048
	ds_read_b128 v[94:97], v94 offset:3072
	ds_read_b128 v[106:109], v134
	ds_read_b128 v[118:121], v134 offset:1024
	ds_read_b128 v[130:133], v134 offset:2048
	ds_read_b128 v[134:137], v134 offset:3072
	s_add_u32 s36, s36, 0x40000
	s_addc_u32 s37, s37, 0
	s_mov_b32 m0, s45
	v_lshl_add_u64 v[228:229], s[36:37], 0, v[182:183]
	ds_read_b128 v[162:165], v204 offset:32768
	ds_read_b128 v[166:169], v204 offset:33792
	ds_read_b128 v[188:191], v204 offset:34816
	ds_read_b128 v[192:195], v204 offset:35840
	ds_read_b128 v[196:199], v204 offset:36864
	ds_read_b128 v[206:209], v204 offset:37888
	ds_read_b128 v[210:213], v204 offset:38912
	ds_read_b128 v[214:217], v204 offset:39936
	global_load_lds_dwordx4 v[228:229], off
	v_lshl_add_u64 v[228:229], s[36:37], 0, v[172:173]
	s_mov_b32 m0, s46
	s_nop 0
	global_load_lds_dwordx4 v[228:229], off
	s_waitcnt vmcnt(8)
	s_waitcnt lgkmcnt(0)
	s_barrier
	s_waitcnt lgkmcnt(0)
	v_mfma_f32_16x16x32_bf16 v[158:161], v[66:69], v[162:165], v[158:161]
	v_mfma_f32_16x16x32_bf16 v[154:157], v[82:85], v[162:165], v[154:157]
	v_mfma_f32_16x16x32_bf16 v[142:145], v[66:69], v[188:191], v[142:145]
	v_mfma_f32_16x16x32_bf16 v[138:141], v[82:85], v[188:191], v[138:141]
	v_mfma_f32_16x16x32_bf16 v[114:117], v[66:69], v[196:199], v[114:117]
	v_mfma_f32_16x16x32_bf16 v[110:113], v[82:85], v[196:199], v[110:113]
	v_mfma_f32_16x16x32_bf16 v[90:93], v[66:69], v[210:213], v[90:93]
	v_mfma_f32_16x16x32_bf16 v[86:89], v[82:85], v[210:213], v[86:89]
	v_mfma_f32_16x16x32_bf16 v[158:161], v[70:73], v[166:169], v[158:161]
	v_mfma_f32_16x16x32_bf16 v[154:157], v[94:97], v[166:169], v[154:157]
	v_mfma_f32_16x16x32_bf16 v[142:145], v[70:73], v[192:195], v[142:145]
	v_mfma_f32_16x16x32_bf16 v[138:141], v[94:97], v[192:195], v[138:141]
	v_mfma_f32_16x16x32_bf16 v[114:117], v[70:73], v[206:209], v[114:117]
	v_mfma_f32_16x16x32_bf16 v[110:113], v[94:97], v[206:209], v[110:113]
	v_mfma_f32_16x16x32_bf16 v[90:93], v[70:73], v[214:217], v[90:93]
	v_mfma_f32_16x16x32_bf16 v[86:89], v[94:97], v[214:217], v[86:89]
	v_mfma_f32_16x16x32_bf16 v[150:153], v[106:109], v[162:165], v[150:153]
	v_mfma_f32_16x16x32_bf16 v[146:149], v[130:133], v[162:165], v[146:149]
	v_mfma_f32_16x16x32_bf16 v[126:129], v[106:109], v[188:191], v[126:129]
	v_mfma_f32_16x16x32_bf16 v[122:125], v[130:133], v[188:191], v[122:125]
	v_mfma_f32_16x16x32_bf16 v[102:105], v[106:109], v[196:199], v[102:105]
	v_mfma_f32_16x16x32_bf16 v[98:101], v[130:133], v[196:199], v[98:101]
	v_mfma_f32_16x16x32_bf16 v[78:81], v[106:109], v[210:213], v[78:81]
	v_mfma_f32_16x16x32_bf16 v[74:77], v[130:133], v[210:213], v[74:77]
	v_mfma_f32_16x16x32_bf16 v[150:153], v[118:121], v[166:169], v[150:153]
	v_mfma_f32_16x16x32_bf16 v[146:149], v[134:137], v[166:169], v[146:149]
	v_mfma_f32_16x16x32_bf16 v[126:129], v[118:121], v[192:195], v[126:129]
	v_mfma_f32_16x16x32_bf16 v[122:125], v[134:137], v[192:195], v[122:125]
	v_mfma_f32_16x16x32_bf16 v[102:105], v[118:121], v[206:209], v[102:105]
	v_mfma_f32_16x16x32_bf16 v[98:101], v[134:137], v[206:209], v[98:101]
	v_mfma_f32_16x16x32_bf16 v[78:81], v[118:121], v[214:217], v[78:81]
	v_mfma_f32_16x16x32_bf16 v[74:77], v[134:137], v[214:217], v[74:77]
	s_barrier
; #define PG8_STAGE(bufoff, gbase, voff) do { _Pragma("unroll") for (int _i = 0; _i < 2; ++_i) \
;         __builtin_amdgcn_global_load_lds((const unsigned*)((const char*)(gbase) + (voff)[_i]), (PG8_LAS unsigned*)(lds + (bufoff) + ldsw + _i * 8192), 16, 0, 0); } while (0)
; #define PG8_LDA(dst, b, h) do { _Pragma("unroll") for (int m = 0; m < 4; ++m) _Pragma("unroll") for (int k = 0; k < 2; ++k) dst[m][k] = *(const PG8_LAS bf16x8*)(lds + PG8_SA(b, h) + aoff + m * 2048 + k * 1024); } while (0)
; #define PG8_MMA(ai, bj, At, Bt) do { __builtin_amdgcn_s_setprio(1); _Pragma("unroll") for (int m = 0; m < 4; ++m) _Pragma("unroll") for (int n = 0; n < 2; ++n) _Pragma("unroll") for (int k = 0; k < 2; ++k) \
;         acc[ai][bj][m][n] = __builtin_amdgcn_mfma_f32_16x16x32_bf16(Bt[n][k], At[m][k], acc[ai][bj][m][n], 0, 0, 0); __builtin_amdgcn_s_setprio(0); } while (0)
; #define PG8_WAIT_V(n) asm volatile("s_waitcnt vmcnt(" #n ")" ::: "memory")
; #define PG8_WAIT_L(n) asm volatile("s_waitcnt lgkmcnt(" #n ")" ::: "memory")
; #define PG8_BAR __builtin_amdgcn_s_barrier()
; #define PG8_SCHED __builtin_amdgcn_sched_barrier(0)
; template <class Epi, class Sched, bool ALIGN_EPI = false, bool SP2 = false>
; __device__ __forceinline__ void gemm_phase(PG8_LAS unsigned char* lds, const Gemm g, const Sched& S, const Epi& E) {
;     ...
;         for (int t = 0; t < nt; t += 2) {
;             const bool last = (t == nt - 2);
;             const char* a1 = cA + (size_t)(t + 1) * kstep;
;             const char* a2 = last ? nA : cA + (size_t)(t + 2) * kstep; const char* b2 = last ? nB : cB + (size_t)(t + 2) * kstep;
;     ...
;             PG8_LDA(At, 1, 1); PG8_STAGE(PG8_SB(1, 0), b3, voffB); PG8_STAGE(PG8_SB(1, 1), b3 + hstep, voffB); PG8_STAGE(PG8_SA(1, 0), a3, voffA);
;             PG8_WAIT_V(8); PG8_WAIT_L(0); PG8_BAR; PG8_MMA(1, 0, At, B0); PG8_MMA(1, 1, At, B1); PG8_BAR; PG8_SCHED;
	s_add_i32 s36, s56, s42
	v_lshl_add_u64 v[200:201], v[200:201], 0, s[96:97]
	s_mov_b32 m0, s36
	ds_read_b128 v[162:165], v204 offset:49152
	ds_read_b128 v[166:169], v204 offset:50176
	ds_read_b128 v[188:191], v204 offset:51200
	ds_read_b128 v[192:195], v204 offset:52224
	ds_read_b128 v[196:199], v204 offset:53248
	ds_read_b128 v[206:209], v204 offset:54272
	ds_read_b128 v[210:213], v204 offset:55296
	ds_read_b128 v[214:217], v204 offset:56320
	global_load_lds_dwordx4 v[200:201], off
	s_add_i32 m0, s36, 0x2000
	s_add_u32 s12, s12, 0x40080
	v_lshl_add_u64 v[200:201], v[218:219], 0, s[96:97]
	s_addc_u32 s13, s13, 0
	s_add_i32 s36, s57, s42
	global_load_lds_dwordx4 v[200:201], off
	v_lshl_add_u64 v[200:201], s[12:13], 0, v[180:181]
	s_mov_b32 m0, s36
	s_nop 0
	global_load_lds_dwordx4 v[200:201], off
	v_lshl_add_u64 v[200:201], s[12:13], 0, v[170:171]
	s_add_i32 m0, s36, 0x2000
	s_nop 0
	global_load_lds_dwordx4 v[200:201], off
	v_lshl_add_u64 v[200:201], v[220:221], 0, s[96:97]
	s_mov_b32 m0, s50
	s_nop 0
	global_load_lds_dwordx4 v[200:201], off
	v_lshl_add_u64 v[200:201], v[222:223], 0, s[96:97]
	s_mov_b32 m0, s51
	s_nop 0
	global_load_lds_dwordx4 v[200:201], off
	s_waitcnt vmcnt(8)
	s_waitcnt lgkmcnt(0)
	s_barrier
	s_waitcnt lgkmcnt(0)
	v_mfma_f32_16x16x32_bf16 v[62:65], v[66:69], v[162:165], v[62:65]
	v_mfma_f32_16x16x32_bf16 v[58:61], v[82:85], v[162:165], v[58:61]
	v_mfma_f32_16x16x32_bf16 v[46:49], v[66:69], v[188:191], v[46:49]
	v_mfma_f32_16x16x32_bf16 v[42:45], v[82:85], v[188:191], v[42:45]
	v_mfma_f32_16x16x32_bf16 v[30:33], v[66:69], v[196:199], v[30:33]
	v_mfma_f32_16x16x32_bf16 v[26:29], v[82:85], v[196:199], v[26:29]
	v_mfma_f32_16x16x32_bf16 v[14:17], v[66:69], v[210:213], v[14:17]
	v_mfma_f32_16x16x32_bf16 v[10:13], v[82:85], v[210:213], v[10:13]
	v_mfma_f32_16x16x32_bf16 v[62:65], v[70:73], v[166:169], v[62:65]
	v_mfma_f32_16x16x32_bf16 v[58:61], v[94:97], v[166:169], v[58:61]
	v_mfma_f32_16x16x32_bf16 v[46:49], v[70:73], v[192:195], v[46:49]
	v_mfma_f32_16x16x32_bf16 v[42:45], v[94:97], v[192:195], v[42:45]
	v_mfma_f32_16x16x32_bf16 v[30:33], v[70:73], v[206:209], v[30:33]
	v_mfma_f32_16x16x32_bf16 v[26:29], v[94:97], v[206:209], v[26:29]
	v_mfma_f32_16x16x32_bf16 v[14:17], v[70:73], v[214:217], v[14:17]
	v_mfma_f32_16x16x32_bf16 v[10:13], v[94:97], v[214:217], v[10:13]
	v_mfma_f32_16x16x32_bf16 v[54:57], v[106:109], v[162:165], v[54:57]
	v_mfma_f32_16x16x32_bf16 v[50:53], v[130:133], v[162:165], v[50:53]
	v_mfma_f32_16x16x32_bf16 v[38:41], v[106:109], v[188:191], v[38:41]
	v_mfma_f32_16x16x32_bf16 v[34:37], v[130:133], v[188:191], v[34:37]
	v_mfma_f32_16x16x32_bf16 v[22:25], v[106:109], v[196:199], v[22:25]
	v_mfma_f32_16x16x32_bf16 v[18:21], v[130:133], v[196:199], v[18:21]
	v_mfma_f32_16x16x32_bf16 v[6:9], v[106:109], v[210:213], v[6:9]
	v_mfma_f32_16x16x32_bf16 v[2:5], v[130:133], v[210:213], v[2:5]
	v_mfma_f32_16x16x32_bf16 v[54:57], v[118:121], v[166:169], v[54:57]
	v_mfma_f32_16x16x32_bf16 v[50:53], v[134:137], v[166:169], v[50:53]
	v_mfma_f32_16x16x32_bf16 v[38:41], v[118:121], v[192:195], v[38:41]
	v_mfma_f32_16x16x32_bf16 v[34:37], v[134:137], v[192:195], v[34:37]
	v_mfma_f32_16x16x32_bf16 v[22:25], v[118:121], v[206:209], v[22:25]
	v_mfma_f32_16x16x32_bf16 v[18:21], v[134:137], v[206:209], v[18:21]
	v_mfma_f32_16x16x32_bf16 v[6:9], v[118:121], v[214:217], v[6:9]
	v_mfma_f32_16x16x32_bf16 v[2:5], v[134:137], v[214:217], v[2:5]
	s_barrier
	s_add_i32 s55, s55, 2
	s_add_u32 s10, s10, 0x100
	s_addc_u32 s11, s11, 0
	s_add_u32 s33, s33, 0x100
	s_addc_u32 s54, s54, 0
	s_cmp_gt_u32 s55, 13
	s_cbranch_scc0 .LBB0_633
	s_and_b64 vcc, exec, s[20:21]
	s_cbranch_vccz .LBB0_636
	s_barrier

; #define PG8_STAGE(bufoff, gbase, voff) do { _Pragma("unroll") for (int _i = 0; _i < 2; ++_i) \
;         __builtin_amdgcn_global_load_lds((const unsigned*)((const char*)(gbase) + (voff)[_i]), (PG8_LAS unsigned*)(lds + (bufoff) + ldsw + _i * 8192), 16, 0, 0); } while (0)
; #define PG8_LDA(dst, b, h) do { _Pragma("unroll") for (int m = 0; m < 4; ++m) _Pragma("unroll") for (int k = 0; k < 2; ++k) dst[m][k] = *(const PG8_LAS bf16x8*)(lds + PG8_SA(b, h) + aoff + m * 2048 + k * 1024); } while (0)
; #define PG8_MMA(ai, bj, At, Bt) do { __builtin_amdgcn_s_setprio(1); _Pragma("unroll") for (int m = 0; m < 4; ++m) _Pragma("unroll") for (int n = 0; n < 2; ++n) _Pragma("unroll") for (int k = 0; k < 2; ++k) \
;         acc[ai][bj][m][n] = __builtin_amdgcn_mfma_f32_16x16x32_bf16(Bt[n][k], At[m][k], acc[ai][bj][m][n], 0, 0, 0); __builtin_amdgcn_s_setprio(0); } while (0)
; #define PG8_WAIT_V(n) asm volatile("s_waitcnt vmcnt(" #n ")" ::: "memory")
; #define PG8_WAIT_L(n) asm volatile("s_waitcnt lgkmcnt(" #n ")" ::: "memory")
; #define PG8_BAR __builtin_amdgcn_s_barrier()
; #define PG8_SCHED __builtin_amdgcn_sched_barrier(0)
; template <class Epi, class Sched, bool ALIGN_EPI = false, bool SP2 = false>
; __device__ __forceinline__ void gemm_phase(PG8_LAS unsigned char* lds, const Gemm g, const Sched& S, const Epi& E) {
;     ...
;             PG8_WAIT_V(8); PG8_WAIT_L(0); PG8_BAR; PG8_MMA(0, 0, At, B0); PG8_MMA(0, 1, At, B1); PG8_BAR; PG8_SCHED;
;             PG8_LDA(At, 0, 1); PG8_STAGE(PG8_SB(0, 0), b2, voffB); PG8_STAGE(PG8_SB(0, 1), b2 + hstep, voffB); PG8_STAGE(PG8_SA(0, 0), a2, voffA);
;             PG8_WAIT_V(8); PG8_WAIT_L(0); PG8_BAR; PG8_MMA(1, 0, At, B0); PG8_MMA(1, 1, At, B1); PG8_BAR; PG8_SCHED;
.Levin_noz:
	s_waitcnt vmcnt(8)
	s_waitcnt lgkmcnt(0)
	s_barrier
	s_waitcnt lgkmcnt(0)
	v_mfma_f32_16x16x32_bf16 v[126:129], v[150:153], v[188:191], v[126:129]
	v_mfma_f32_16x16x32_bf16 v[122:125], v[158:161], v[188:191], v[122:125]
	v_mfma_f32_16x16x32_bf16 v[114:117], v[150:153], v[196:199], v[114:117]
	v_mfma_f32_16x16x32_bf16 v[106:109], v[158:161], v[196:199], v[106:109]
	v_mfma_f32_16x16x32_bf16 v[98:101], v[150:153], v[204:207], v[98:101]
	v_mfma_f32_16x16x32_bf16 v[90:93], v[158:161], v[204:207], v[90:93]
	v_mfma_f32_16x16x32_bf16 v[82:85], v[150:153], v[212:215], v[82:85]
	v_mfma_f32_16x16x32_bf16 v[74:77], v[158:161], v[212:215], v[74:77]
	v_mfma_f32_16x16x32_bf16 v[126:129], v[154:157], v[192:195], v[126:129]
	v_mfma_f32_16x16x32_bf16 v[122:125], v[162:165], v[192:195], v[122:125]
	v_mfma_f32_16x16x32_bf16 v[114:117], v[154:157], v[200:203], v[114:117]
	v_mfma_f32_16x16x32_bf16 v[106:109], v[162:165], v[200:203], v[106:109]
	v_mfma_f32_16x16x32_bf16 v[98:101], v[154:157], v[208:211], v[98:101]
	v_mfma_f32_16x16x32_bf16 v[90:93], v[162:165], v[208:211], v[90:93]
	v_mfma_f32_16x16x32_bf16 v[82:85], v[154:157], v[216:219], v[82:85]
	v_mfma_f32_16x16x32_bf16 v[74:77], v[162:165], v[216:219], v[74:77]
	v_mfma_f32_16x16x32_bf16 v[118:121], v[166:169], v[188:191], v[118:121]
	v_mfma_f32_16x16x32_bf16 v[110:113], v[180:183], v[188:191], v[110:113]
	v_mfma_f32_16x16x32_bf16 v[102:105], v[166:169], v[196:199], v[102:105]
	v_mfma_f32_16x16x32_bf16 v[94:97], v[180:183], v[196:199], v[94:97]
	v_mfma_f32_16x16x32_bf16 v[86:89], v[166:169], v[204:207], v[86:89]
	v_mfma_f32_16x16x32_bf16 v[78:81], v[180:183], v[204:207], v[78:81]
	v_mfma_f32_16x16x32_bf16 v[70:73], v[166:169], v[212:215], v[70:73]
	v_mfma_f32_16x16x32_bf16 v[66:69], v[180:183], v[212:215], v[66:69]
	v_mfma_f32_16x16x32_bf16 v[118:121], v[170:173], v[192:195], v[118:121]
	v_mfma_f32_16x16x32_bf16 v[110:113], v[184:187], v[192:195], v[110:113]
	v_mfma_f32_16x16x32_bf16 v[102:105], v[170:173], v[200:203], v[102:105]
	v_mfma_f32_16x16x32_bf16 v[94:97], v[184:187], v[200:203], v[94:97]
	v_mfma_f32_16x16x32_bf16 v[86:89], v[170:173], v[208:211], v[86:89]
	v_mfma_f32_16x16x32_bf16 v[78:81], v[184:187], v[208:211], v[78:81]
	v_mfma_f32_16x16x32_bf16 v[70:73], v[170:173], v[216:219], v[70:73]
	v_mfma_f32_16x16x32_bf16 v[66:69], v[184:187], v[216:219], v[66:69]
	s_barrier
	s_add_i32 s49, s49, s35
	v_lshl_add_u64 v[146:147], s[26:27], 0, v[134:135]
	s_mov_b32 m0, s49
	ds_read_b128 v[188:191], v149 offset:16384
	ds_read_b128 v[192:195], v149 offset:17408
	ds_read_b128 v[196:199], v149 offset:18432
	ds_read_b128 v[200:203], v149 offset:19456
	ds_read_b128 v[204:207], v149 offset:20480
	ds_read_b128 v[208:211], v149 offset:21504
	ds_read_b128 v[212:215], v149 offset:22528
	ds_read_b128 v[216:219], v149 offset:23552
	global_load_lds_dwordx4 v[146:147], off
	s_add_i32 m0, s49, 0x2000
	s_add_u32 s50, s26, 0x40000
	v_lshl_add_u64 v[220:221], s[26:27], 0, v[130:131]
	s_addc_u32 s51, s27, 0
	s_add_i32 s49, s52, s35
	global_load_lds_dwordx4 v[220:221], off
	v_lshl_add_u64 v[222:223], s[50:51], 0, v[134:135]
	s_mov_b32 m0, s49
	v_lshl_add_u64 v[228:229], s[28:29], 0, v[132:133]
	global_load_lds_dwordx4 v[222:223], off
	v_lshl_add_u64 v[222:223], s[50:51], 0, v[130:131]
	s_add_i32 m0, s49, 0x2000
	s_nop 0
	global_load_lds_dwordx4 v[222:223], off
	v_lshl_add_u64 v[222:223], s[28:29], 0, v[136:137]
	s_mov_b32 m0, s36
	s_nop 0
	global_load_lds_dwordx4 v[222:223], off
	s_mov_b32 m0, s37
	s_nop 0
	global_load_lds_dwordx4 v[228:229], off
	s_waitcnt vmcnt(8)
	s_waitcnt lgkmcnt(0)
	s_barrier
	s_waitcnt lgkmcnt(0)
	v_mfma_f32_16x16x32_bf16 v[62:65], v[150:153], v[188:191], v[62:65]
	v_mfma_f32_16x16x32_bf16 v[58:61], v[158:161], v[188:191], v[58:61]
	v_mfma_f32_16x16x32_bf16 v[50:53], v[150:153], v[196:199], v[50:53]
	v_mfma_f32_16x16x32_bf16 v[42:45], v[158:161], v[196:199], v[42:45]
	v_mfma_f32_16x16x32_bf16 v[34:37], v[150:153], v[204:207], v[34:37]
	v_mfma_f32_16x16x32_bf16 v[26:29], v[158:161], v[204:207], v[26:29]
	v_mfma_f32_16x16x32_bf16 v[18:21], v[150:153], v[212:215], v[18:21]
	v_mfma_f32_16x16x32_bf16 v[10:13], v[158:161], v[212:215], v[10:13]
	v_mfma_f32_16x16x32_bf16 v[62:65], v[154:157], v[192:195], v[62:65]
	v_mfma_f32_16x16x32_bf16 v[58:61], v[162:165], v[192:195], v[58:61]
	v_mfma_f32_16x16x32_bf16 v[50:53], v[154:157], v[200:203], v[50:53]
	v_mfma_f32_16x16x32_bf16 v[42:45], v[162:165], v[200:203], v[42:45]
	v_mfma_f32_16x16x32_bf16 v[34:37], v[154:157], v[208:211], v[34:37]
	v_mfma_f32_16x16x32_bf16 v[26:29], v[162:165], v[208:211], v[26:29]
	v_mfma_f32_16x16x32_bf16 v[18:21], v[154:157], v[216:219], v[18:21]
	v_mfma_f32_16x16x32_bf16 v[10:13], v[162:165], v[216:219], v[10:13]
	v_mfma_f32_16x16x32_bf16 v[54:57], v[166:169], v[188:191], v[54:57]
	v_mfma_f32_16x16x32_bf16 v[46:49], v[180:183], v[188:191], v[46:49]
	v_mfma_f32_16x16x32_bf16 v[38:41], v[166:169], v[196:199], v[38:41]
	v_mfma_f32_16x16x32_bf16 v[30:33], v[180:183], v[196:199], v[30:33]
	v_mfma_f32_16x16x32_bf16 v[22:25], v[166:169], v[204:207], v[22:25]
	v_mfma_f32_16x16x32_bf16 v[14:17], v[180:183], v[204:207], v[14:17]
	v_mfma_f32_16x16x32_bf16 v[6:9], v[166:169], v[212:215], v[6:9]
	v_mfma_f32_16x16x32_bf16 v[2:5], v[180:183], v[212:215], v[2:5]
	v_mfma_f32_16x16x32_bf16 v[54:57], v[170:173], v[192:195], v[54:57]
	v_mfma_f32_16x16x32_bf16 v[46:49], v[184:187], v[192:195], v[46:49]
	v_mfma_f32_16x16x32_bf16 v[38:41], v[170:173], v[200:203], v[38:41]
	v_mfma_f32_16x16x32_bf16 v[30:33], v[184:187], v[200:203], v[30:33]
	v_mfma_f32_16x16x32_bf16 v[22:25], v[170:173], v[208:211], v[22:25]
	v_mfma_f32_16x16x32_bf16 v[14:17], v[184:187], v[208:211], v[14:17]
	v_mfma_f32_16x16x32_bf16 v[6:9], v[170:173], v[216:219], v[6:9]
	v_mfma_f32_16x16x32_bf16 v[2:5], v[184:187], v[216:219], v[2:5]
	s_barrier
; #define PG8_STAGE(bufoff, gbase, voff) do { _Pragma("unroll") for (int _i = 0; _i < 2; ++_i) \
;         __builtin_amdgcn_global_load_lds((const unsigned*)((const char*)(gbase) + (voff)[_i]), (PG8_LAS unsigned*)(lds + (bufoff) + ldsw + _i * 8192), 16, 0, 0); } while (0)
; #define PG8_LDA(dst, b, h) do { _Pragma("unroll") for (int m = 0; m < 4; ++m) _Pragma("unroll") for (int k = 0; k < 2; ++k) dst[m][k] = *(const PG8_LAS bf16x8*)(lds + PG8_SA(b, h) + aoff + m * 2048 + k * 1024); } while (0)
; #define PG8_LDB(dst, b, h) do { _Pragma("unroll") for (int n = 0; n < 2; ++n) _Pragma("unroll") for (int k = 0; k < 2; ++k) dst[n][k] = *(const PG8_LAS bf16x8*)(lds + PG8_SB(b, h) + boff + n * 2048 + k * 1024); } while (0)
; #define PG8_MMA(ai, bj, At, Bt) do { __builtin_amdgcn_s_setprio(1); _Pragma("unroll") for (int m = 0; m < 4; ++m) _Pragma("unroll") for (int n = 0; n < 2; ++n) _Pragma("unroll") for (int k = 0; k < 2; ++k) \
;         acc[ai][bj][m][n] = __builtin_amdgcn_mfma_f32_16x16x32_bf16(Bt[n][k], At[m][k], acc[ai][bj][m][n], 0, 0, 0); __builtin_amdgcn_s_setprio(0); } while (0)
; #define PG8_WAIT_V(n) asm volatile("s_waitcnt vmcnt(" #n ")" ::: "memory")
; #define PG8_WAIT_L(n) asm volatile("s_waitcnt lgkmcnt(" #n ")" ::: "memory")
; #define PG8_BAR __builtin_amdgcn_s_barrier()
; #define PG8_SCHED __builtin_amdgcn_sched_barrier(0)
; template <class Epi, class Sched, bool ALIGN_EPI = false, bool SP2 = false>
; __device__ __forceinline__ void gemm_phase(PG8_LAS unsigned char* lds, const Gemm g, const Sched& S, const Epi& E) {
;     ...
;             PG8_LDB(B0, 1, 0); PG8_LDB(B1, 1, 1); PG8_SCHED; PG8_LDA(At, 1, 0); PG8_STAGE(PG8_SA(0, 1), a2 + hstep, voffA);
;             PG8_WAIT_V(8); PG8_WAIT_L(0); PG8_BAR; PG8_MMA(0, 0, At, B0); PG8_MMA(0, 1, At, B1); PG8_BAR; PG8_SCHED;
	s_add_i32 s49, 0, 0x18000
	v_add_u32_e32 v142, s49, v145
	s_add_i32 s50, 0, 0x1c000
	ds_read_b128 v[150:153], v142
	ds_read_b128 v[154:157], v142 offset:1024
	ds_read_b128 v[158:161], v142 offset:2048
	ds_read_b128 v[162:165], v142 offset:3072
	v_add_u32_e32 v142, s50, v145
	ds_read_b128 v[166:169], v142
	ds_read_b128 v[170:173], v142 offset:1024
	ds_read_b128 v[180:183], v142 offset:2048
	ds_read_b128 v[184:187], v142 offset:3072
	s_add_u32 s28, s28, 0x40000
	s_addc_u32 s29, s29, 0
	s_mov_b32 m0, s38
	v_lshl_add_u64 v[230:231], s[28:29], 0, v[136:137]
	ds_read_b128 v[188:191], v149 offset:32768
	ds_read_b128 v[192:195], v149 offset:33792
	ds_read_b128 v[196:199], v149 offset:34816
	ds_read_b128 v[200:203], v149 offset:35840
	ds_read_b128 v[204:207], v149 offset:36864
	ds_read_b128 v[208:211], v149 offset:37888
	ds_read_b128 v[212:215], v149 offset:38912
	ds_read_b128 v[216:219], v149 offset:39936
	global_load_lds_dwordx4 v[230:231], off
	v_lshl_add_u64 v[230:231], s[28:29], 0, v[132:133]
	s_mov_b32 m0, s39
	s_nop 0
	global_load_lds_dwordx4 v[230:231], off
	s_waitcnt vmcnt(8)
	s_waitcnt lgkmcnt(0)
	s_barrier
	s_waitcnt lgkmcnt(0)
	v_mfma_f32_16x16x32_bf16 v[126:129], v[150:153], v[188:191], v[126:129]
	v_mfma_f32_16x16x32_bf16 v[122:125], v[158:161], v[188:191], v[122:125]
	v_mfma_f32_16x16x32_bf16 v[114:117], v[150:153], v[196:199], v[114:117]
	v_mfma_f32_16x16x32_bf16 v[106:109], v[158:161], v[196:199], v[106:109]
	v_mfma_f32_16x16x32_bf16 v[98:101], v[150:153], v[204:207], v[98:101]
	v_mfma_f32_16x16x32_bf16 v[90:93], v[158:161], v[204:207], v[90:93]
	v_mfma_f32_16x16x32_bf16 v[82:85], v[150:153], v[212:215], v[82:85]
	v_mfma_f32_16x16x32_bf16 v[74:77], v[158:161], v[212:215], v[74:77]
	v_mfma_f32_16x16x32_bf16 v[126:129], v[154:157], v[192:195], v[126:129]
	v_mfma_f32_16x16x32_bf16 v[122:125], v[162:165], v[192:195], v[122:125]
	v_mfma_f32_16x16x32_bf16 v[114:117], v[154:157], v[200:203], v[114:117]
	v_mfma_f32_16x16x32_bf16 v[106:109], v[162:165], v[200:203], v[106:109]
	v_mfma_f32_16x16x32_bf16 v[98:101], v[154:157], v[208:211], v[98:101]
	v_mfma_f32_16x16x32_bf16 v[90:93], v[162:165], v[208:211], v[90:93]
	v_mfma_f32_16x16x32_bf16 v[82:85], v[154:157], v[216:219], v[82:85]
	v_mfma_f32_16x16x32_bf16 v[74:77], v[162:165], v[216:219], v[74:77]
	v_mfma_f32_16x16x32_bf16 v[118:121], v[166:169], v[188:191], v[118:121]
	v_mfma_f32_16x16x32_bf16 v[110:113], v[180:183], v[188:191], v[110:113]
	v_mfma_f32_16x16x32_bf16 v[102:105], v[166:169], v[196:199], v[102:105]
	v_mfma_f32_16x16x32_bf16 v[94:97], v[180:183], v[196:199], v[94:97]
	v_mfma_f32_16x16x32_bf16 v[86:89], v[166:169], v[204:207], v[86:89]
	v_mfma_f32_16x16x32_bf16 v[78:81], v[180:183], v[204:207], v[78:81]
	v_mfma_f32_16x16x32_bf16 v[70:73], v[166:169], v[212:215], v[70:73]
	v_mfma_f32_16x16x32_bf16 v[66:69], v[180:183], v[212:215], v[66:69]
	v_mfma_f32_16x16x32_bf16 v[118:121], v[170:173], v[192:195], v[118:121]
	v_mfma_f32_16x16x32_bf16 v[110:113], v[184:187], v[192:195], v[110:113]
	v_mfma_f32_16x16x32_bf16 v[102:105], v[170:173], v[200:203], v[102:105]
	v_mfma_f32_16x16x32_bf16 v[94:97], v[184:187], v[200:203], v[94:97]
	v_mfma_f32_16x16x32_bf16 v[86:89], v[170:173], v[208:211], v[86:89]
	v_mfma_f32_16x16x32_bf16 v[78:81], v[184:187], v[208:211], v[78:81]
	v_mfma_f32_16x16x32_bf16 v[70:73], v[170:173], v[216:219], v[70:73]
	v_mfma_f32_16x16x32_bf16 v[66:69], v[184:187], v[216:219], v[66:69]
	s_barrier
; #define PG8_STAGE(bufoff, gbase, voff) do { _Pragma("unroll") for (int _i = 0; _i < 2; ++_i) \
;         __builtin_amdgcn_global_load_lds((const unsigned*)((const char*)(gbase) + (voff)[_i]), (PG8_LAS unsigned*)(lds + (bufoff) + ldsw + _i * 8192), 16, 0, 0); } while (0)
; #define PG8_LDA(dst, b, h) do { _Pragma("unroll") for (int m = 0; m < 4; ++m) _Pragma("unroll") for (int k = 0; k < 2; ++k) dst[m][k] = *(const PG8_LAS bf16x8*)(lds + PG8_SA(b, h) + aoff + m * 2048 + k * 1024); } while (0)
; #define PG8_MMA(ai, bj, At, Bt) do { __builtin_amdgcn_s_setprio(1); _Pragma("unroll") for (int m = 0; m < 4; ++m) _Pragma("unroll") for (int n = 0; n < 2; ++n) _Pragma("unroll") for (int k = 0; k < 2; ++k) \
;         acc[ai][bj][m][n] = __builtin_amdgcn_mfma_f32_16x16x32_bf16(Bt[n][k], At[m][k], acc[ai][bj][m][n], 0, 0, 0); __builtin_amdgcn_s_setprio(0); } while (0)
; #define PG8_WAIT_V(n) asm volatile("s_waitcnt vmcnt(" #n ")" ::: "memory")
; #define PG8_WAIT_L(n) asm volatile("s_waitcnt lgkmcnt(" #n ")" ::: "memory")
; #define PG8_BAR __builtin_amdgcn_s_barrier()
; #define PG8_SCHED __builtin_amdgcn_sched_barrier(0)
; template <class Epi, class Sched, bool ALIGN_EPI = false, bool SP2 = false>
; __device__ __forceinline__ void gemm_phase(PG8_LAS unsigned char* lds, const Gemm g, const Sched& S, const Epi& E) {
;     ...
;         for (int t = 0; t < nt; t += 2) {
;             const bool last = (t == nt - 2);
;             const char* a1 = cA + (size_t)(t + 1) * kstep;
;             const char* a2 = last ? nA : cA + (size_t)(t + 2) * kstep; const char* b2 = last ? nB : cB + (size_t)(t + 2) * kstep;
;     ...
;             PG8_LDA(At, 1, 1); PG8_STAGE(PG8_SB(1, 0), b3, voffB); PG8_STAGE(PG8_SB(1, 1), b3 + hstep, voffB); PG8_STAGE(PG8_SA(1, 0), a3, voffA);
;             PG8_WAIT_V(8); PG8_WAIT_L(0); PG8_BAR; PG8_MMA(1, 0, At, B0); PG8_MMA(1, 1, At, B1); PG8_BAR; PG8_SCHED;
	s_add_i32 s28, s49, s35
	v_lshl_add_u64 v[146:147], v[146:147], 0, s[96:97]
	s_mov_b32 m0, s28
	ds_read_b128 v[188:191], v149 offset:49152
	ds_read_b128 v[192:195], v149 offset:50176
	ds_read_b128 v[196:199], v149 offset:51200
	ds_read_b128 v[200:203], v149 offset:52224
	ds_read_b128 v[204:207], v149 offset:53248
	ds_read_b128 v[208:211], v149 offset:54272
	ds_read_b128 v[212:215], v149 offset:55296
	ds_read_b128 v[216:219], v149 offset:56320
	global_load_lds_dwordx4 v[146:147], off
	s_add_i32 m0, s28, 0x2000
	s_add_u32 s26, s26, 0x40080
	v_lshl_add_u64 v[146:147], v[220:221], 0, s[96:97]
	s_addc_u32 s27, s27, 0
	s_add_i32 s28, s50, s35
	global_load_lds_dwordx4 v[146:147], off
	v_lshl_add_u64 v[146:147], s[26:27], 0, v[134:135]
	s_mov_b32 m0, s28
	s_nop 0
	global_load_lds_dwordx4 v[146:147], off
	v_lshl_add_u64 v[146:147], s[26:27], 0, v[130:131]
	s_add_i32 m0, s28, 0x2000
	s_nop 0
	global_load_lds_dwordx4 v[146:147], off
	v_lshl_add_u64 v[146:147], v[222:223], 0, s[96:97]
	s_mov_b32 m0, s42
	s_nop 0
	global_load_lds_dwordx4 v[146:147], off
	v_lshl_add_u64 v[146:147], v[228:229], 0, s[96:97]
	s_mov_b32 m0, s43
	s_nop 0
	global_load_lds_dwordx4 v[146:147], off
	s_waitcnt vmcnt(8)
	s_waitcnt lgkmcnt(0)
	s_barrier
	s_waitcnt lgkmcnt(0)
	v_mfma_f32_16x16x32_bf16 v[62:65], v[150:153], v[188:191], v[62:65]
	v_mfma_f32_16x16x32_bf16 v[58:61], v[158:161], v[188:191], v[58:61]
	v_mfma_f32_16x16x32_bf16 v[50:53], v[150:153], v[196:199], v[50:53]
	v_mfma_f32_16x16x32_bf16 v[42:45], v[158:161], v[196:199], v[42:45]
	v_mfma_f32_16x16x32_bf16 v[34:37], v[150:153], v[204:207], v[34:37]
	v_mfma_f32_16x16x32_bf16 v[26:29], v[158:161], v[204:207], v[26:29]
	v_mfma_f32_16x16x32_bf16 v[18:21], v[150:153], v[212:215], v[18:21]
	v_mfma_f32_16x16x32_bf16 v[10:13], v[158:161], v[212:215], v[10:13]
	v_mfma_f32_16x16x32_bf16 v[62:65], v[154:157], v[192:195], v[62:65]
	v_mfma_f32_16x16x32_bf16 v[58:61], v[162:165], v[192:195], v[58:61]
	v_mfma_f32_16x16x32_bf16 v[50:53], v[154:157], v[200:203], v[50:53]
	v_mfma_f32_16x16x32_bf16 v[42:45], v[162:165], v[200:203], v[42:45]
	v_mfma_f32_16x16x32_bf16 v[34:37], v[154:157], v[208:211], v[34:37]
	v_mfma_f32_16x16x32_bf16 v[26:29], v[162:165], v[208:211], v[26:29]
	v_mfma_f32_16x16x32_bf16 v[18:21], v[154:157], v[216:219], v[18:21]
	v_mfma_f32_16x16x32_bf16 v[10:13], v[162:165], v[216:219], v[10:13]
	v_mfma_f32_16x16x32_bf16 v[54:57], v[166:169], v[188:191], v[54:57]
	v_mfma_f32_16x16x32_bf16 v[46:49], v[180:183], v[188:191], v[46:49]
	v_mfma_f32_16x16x32_bf16 v[38:41], v[166:169], v[196:199], v[38:41]
	v_mfma_f32_16x16x32_bf16 v[30:33], v[180:183], v[196:199], v[30:33]
	v_mfma_f32_16x16x32_bf16 v[22:25], v[166:169], v[204:207], v[22:25]
	v_mfma_f32_16x16x32_bf16 v[14:17], v[180:183], v[204:207], v[14:17]
	v_mfma_f32_16x16x32_bf16 v[6:9], v[166:169], v[212:215], v[6:9]
	v_mfma_f32_16x16x32_bf16 v[2:5], v[180:183], v[212:215], v[2:5]
	v_mfma_f32_16x16x32_bf16 v[54:57], v[170:173], v[192:195], v[54:57]
	v_mfma_f32_16x16x32_bf16 v[46:49], v[184:187], v[192:195], v[46:49]
	v_mfma_f32_16x16x32_bf16 v[38:41], v[170:173], v[200:203], v[38:41]
	v_mfma_f32_16x16x32_bf16 v[30:33], v[184:187], v[200:203], v[30:33]
	v_mfma_f32_16x16x32_bf16 v[22:25], v[170:173], v[208:211], v[22:25]
	v_mfma_f32_16x16x32_bf16 v[14:17], v[184:187], v[208:211], v[14:17]
	v_mfma_f32_16x16x32_bf16 v[6:9], v[170:173], v[216:219], v[6:9]
	v_mfma_f32_16x16x32_bf16 v[2:5], v[184:187], v[216:219], v[2:5]
	s_barrier
	s_add_i32 s48, s48, 2
	s_add_u32 s24, s24, 0x100
	s_addc_u32 s25, s25, 0
	s_add_u32 s46, s46, 0x100
	s_addc_u32 s47, s47, 0
	s_cmp_gt_u32 s48, 13
	s_cbranch_scc0 .LBB0_812
	s_and_b64 vcc, exec, s[14:15]
	s_cbranch_vccz .LBB0_815
	s_barrier

; #define PG8_STAGE(bufoff, gbase, voff) do { _Pragma("unroll") for (int _i = 0; _i < 2; ++_i) \
;         __builtin_amdgcn_global_load_lds((const unsigned*)((const char*)(gbase) + (voff)[_i]), (PG8_LAS unsigned*)(lds + (bufoff) + ldsw + _i * 8192), 16, 0, 0); } while (0)
; #define PG8_LDA(dst, b, h) do { _Pragma("unroll") for (int m = 0; m < 4; ++m) _Pragma("unroll") for (int k = 0; k < 2; ++k) dst[m][k] = *(const PG8_LAS bf16x8*)(lds + PG8_SA(b, h) + aoff + m * 2048 + k * 1024); } while (0)
; #define PG8_MMA(ai, bj, At, Bt) do { __builtin_amdgcn_s_setprio(1); _Pragma("unroll") for (int m = 0; m < 4; ++m) _Pragma("unroll") for (int n = 0; n < 2; ++n) _Pragma("unroll") for (int k = 0; k < 2; ++k) \
;         acc[ai][bj][m][n] = __builtin_amdgcn_mfma_f32_16x16x32_bf16(Bt[n][k], At[m][k], acc[ai][bj][m][n], 0, 0, 0); __builtin_amdgcn_s_setprio(0); } while (0)
; #define PG8_WAIT_V(n) asm volatile("s_waitcnt vmcnt(" #n ")" ::: "memory")
; #define PG8_WAIT_L(n) asm volatile("s_waitcnt lgkmcnt(" #n ")" ::: "memory")
; #define PG8_BAR __builtin_amdgcn_s_barrier()
; #define PG8_SCHED __builtin_amdgcn_sched_barrier(0)
; template <class Epi, class Sched, bool ALIGN_EPI = false, bool SP2 = false>
; __device__ __forceinline__ void gemm_phase(PG8_LAS unsigned char* lds, const Gemm g, const Sched& S, const Epi& E) {
;     ...
;             PG8_WAIT_V(8); PG8_WAIT_L(0); PG8_BAR; PG8_MMA(0, 0, At, B0); PG8_MMA(0, 1, At, B1); PG8_BAR; PG8_SCHED;
;             PG8_LDA(At, 0, 1); PG8_STAGE(PG8_SB(0, 0), b2, voffB); PG8_STAGE(PG8_SB(0, 1), b2 + hstep, voffB); PG8_STAGE(PG8_SA(0, 0), a2, voffA);
;             PG8_WAIT_V(8); PG8_WAIT_L(0); PG8_BAR; PG8_MMA(1, 0, At, B0); PG8_MMA(1, 1, At, B1); PG8_BAR; PG8_SCHED;
.Levout_noz:
	s_waitcnt vmcnt(8)
	s_waitcnt lgkmcnt(0)
	s_barrier
	s_waitcnt lgkmcnt(0)
	v_mfma_f32_16x16x32_bf16 v[158:161], v[66:69], v[162:165], v[158:161]
	v_mfma_f32_16x16x32_bf16 v[154:157], v[82:85], v[162:165], v[154:157]
	v_mfma_f32_16x16x32_bf16 v[142:145], v[66:69], v[188:191], v[142:145]
	v_mfma_f32_16x16x32_bf16 v[138:141], v[82:85], v[188:191], v[138:141]
	v_mfma_f32_16x16x32_bf16 v[114:117], v[66:69], v[196:199], v[114:117]
	v_mfma_f32_16x16x32_bf16 v[110:113], v[82:85], v[196:199], v[110:113]
	v_mfma_f32_16x16x32_bf16 v[90:93], v[66:69], v[210:213], v[90:93]
	v_mfma_f32_16x16x32_bf16 v[86:89], v[82:85], v[210:213], v[86:89]
	v_mfma_f32_16x16x32_bf16 v[158:161], v[70:73], v[166:169], v[158:161]
	v_mfma_f32_16x16x32_bf16 v[154:157], v[94:97], v[166:169], v[154:157]
	v_mfma_f32_16x16x32_bf16 v[142:145], v[70:73], v[192:195], v[142:145]
	v_mfma_f32_16x16x32_bf16 v[138:141], v[94:97], v[192:195], v[138:141]
	v_mfma_f32_16x16x32_bf16 v[114:117], v[70:73], v[206:209], v[114:117]
	v_mfma_f32_16x16x32_bf16 v[110:113], v[94:97], v[206:209], v[110:113]
	v_mfma_f32_16x16x32_bf16 v[90:93], v[70:73], v[214:217], v[90:93]
	v_mfma_f32_16x16x32_bf16 v[86:89], v[94:97], v[214:217], v[86:89]
	v_mfma_f32_16x16x32_bf16 v[150:153], v[106:109], v[162:165], v[150:153]
	v_mfma_f32_16x16x32_bf16 v[146:149], v[130:133], v[162:165], v[146:149]
	v_mfma_f32_16x16x32_bf16 v[126:129], v[106:109], v[188:191], v[126:129]
	v_mfma_f32_16x16x32_bf16 v[122:125], v[130:133], v[188:191], v[122:125]
	v_mfma_f32_16x16x32_bf16 v[102:105], v[106:109], v[196:199], v[102:105]
	v_mfma_f32_16x16x32_bf16 v[98:101], v[130:133], v[196:199], v[98:101]
	v_mfma_f32_16x16x32_bf16 v[78:81], v[106:109], v[210:213], v[78:81]
	v_mfma_f32_16x16x32_bf16 v[74:77], v[130:133], v[210:213], v[74:77]
	v_mfma_f32_16x16x32_bf16 v[150:153], v[118:121], v[166:169], v[150:153]
	v_mfma_f32_16x16x32_bf16 v[146:149], v[134:137], v[166:169], v[146:149]
	v_mfma_f32_16x16x32_bf16 v[126:129], v[118:121], v[192:195], v[126:129]
	v_mfma_f32_16x16x32_bf16 v[122:125], v[134:137], v[192:195], v[122:125]
	v_mfma_f32_16x16x32_bf16 v[102:105], v[118:121], v[206:209], v[102:105]
	v_mfma_f32_16x16x32_bf16 v[98:101], v[134:137], v[206:209], v[98:101]
	v_mfma_f32_16x16x32_bf16 v[78:81], v[118:121], v[214:217], v[78:81]
	v_mfma_f32_16x16x32_bf16 v[74:77], v[134:137], v[214:217], v[74:77]
	s_barrier
	s_add_i32 s56, s56, s42
	v_lshl_add_u64 v[200:201], s[10:11], 0, v[180:181]
	s_mov_b32 m0, s56
	ds_read_b128 v[162:165], v204 offset:16384
	ds_read_b128 v[166:169], v204 offset:17408
	ds_read_b128 v[188:191], v204 offset:18432
	ds_read_b128 v[192:195], v204 offset:19456
	ds_read_b128 v[196:199], v204 offset:20480
	ds_read_b128 v[206:209], v204 offset:21504
	ds_read_b128 v[210:213], v204 offset:22528
	ds_read_b128 v[214:217], v204 offset:23552
	global_load_lds_dwordx4 v[200:201], off
	s_add_i32 m0, s56, 0x2000
	s_add_u32 s56, s10, 0x40000
	v_lshl_add_u64 v[218:219], s[10:11], 0, v[170:171]
	s_addc_u32 s57, s11, 0
	s_add_i32 s58, s58, s42
	global_load_lds_dwordx4 v[218:219], off
	v_lshl_add_u64 v[220:221], s[56:57], 0, v[180:181]
	s_mov_b32 m0, s58
	v_lshl_add_u64 v[222:223], s[36:37], 0, v[172:173]
	global_load_lds_dwordx4 v[220:221], off
	v_lshl_add_u64 v[220:221], s[56:57], 0, v[170:171]
	s_add_i32 m0, s58, 0x2000
	s_nop 0
	global_load_lds_dwordx4 v[220:221], off
	v_lshl_add_u64 v[220:221], s[36:37], 0, v[182:183]
	s_mov_b32 m0, s43
	s_nop 0
	global_load_lds_dwordx4 v[220:221], off
	s_mov_b32 m0, s44
	s_nop 0
	global_load_lds_dwordx4 v[222:223], off
	s_waitcnt vmcnt(8)
	s_waitcnt lgkmcnt(0)
	s_barrier
	s_waitcnt lgkmcnt(0)
	v_mfma_f32_16x16x32_bf16 v[62:65], v[66:69], v[162:165], v[62:65]
	v_mfma_f32_16x16x32_bf16 v[58:61], v[82:85], v[162:165], v[58:61]
	v_mfma_f32_16x16x32_bf16 v[46:49], v[66:69], v[188:191], v[46:49]
	v_mfma_f32_16x16x32_bf16 v[42:45], v[82:85], v[188:191], v[42:45]
	v_mfma_f32_16x16x32_bf16 v[30:33], v[66:69], v[196:199], v[30:33]
	v_mfma_f32_16x16x32_bf16 v[26:29], v[82:85], v[196:199], v[26:29]
	v_mfma_f32_16x16x32_bf16 v[14:17], v[66:69], v[210:213], v[14:17]
	v_mfma_f32_16x16x32_bf16 v[10:13], v[82:85], v[210:213], v[10:13]
	v_mfma_f32_16x16x32_bf16 v[62:65], v[70:73], v[166:169], v[62:65]
	v_mfma_f32_16x16x32_bf16 v[58:61], v[94:97], v[166:169], v[58:61]
	v_mfma_f32_16x16x32_bf16 v[46:49], v[70:73], v[192:195], v[46:49]
	v_mfma_f32_16x16x32_bf16 v[42:45], v[94:97], v[192:195], v[42:45]
	v_mfma_f32_16x16x32_bf16 v[30:33], v[70:73], v[206:209], v[30:33]
	v_mfma_f32_16x16x32_bf16 v[26:29], v[94:97], v[206:209], v[26:29]
	v_mfma_f32_16x16x32_bf16 v[14:17], v[70:73], v[214:217], v[14:17]
	v_mfma_f32_16x16x32_bf16 v[10:13], v[94:97], v[214:217], v[10:13]
	v_mfma_f32_16x16x32_bf16 v[54:57], v[106:109], v[162:165], v[54:57]
	v_mfma_f32_16x16x32_bf16 v[50:53], v[130:133], v[162:165], v[50:53]
	v_mfma_f32_16x16x32_bf16 v[38:41], v[106:109], v[188:191], v[38:41]
	v_mfma_f32_16x16x32_bf16 v[34:37], v[130:133], v[188:191], v[34:37]
	v_mfma_f32_16x16x32_bf16 v[22:25], v[106:109], v[196:199], v[22:25]
	v_mfma_f32_16x16x32_bf16 v[18:21], v[130:133], v[196:199], v[18:21]
	v_mfma_f32_16x16x32_bf16 v[6:9], v[106:109], v[210:213], v[6:9]
	v_mfma_f32_16x16x32_bf16 v[2:5], v[130:133], v[210:213], v[2:5]
	v_mfma_f32_16x16x32_bf16 v[54:57], v[118:121], v[166:169], v[54:57]
	v_mfma_f32_16x16x32_bf16 v[50:53], v[134:137], v[166:169], v[50:53]
	v_mfma_f32_16x16x32_bf16 v[38:41], v[118:121], v[192:195], v[38:41]
	v_mfma_f32_16x16x32_bf16 v[34:37], v[134:137], v[192:195], v[34:37]
	v_mfma_f32_16x16x32_bf16 v[22:25], v[118:121], v[206:209], v[22:25]
	v_mfma_f32_16x16x32_bf16 v[18:21], v[134:137], v[206:209], v[18:21]
	v_mfma_f32_16x16x32_bf16 v[6:9], v[118:121], v[214:217], v[6:9]
	v_mfma_f32_16x16x32_bf16 v[2:5], v[134:137], v[214:217], v[2:5]
	s_barrier
; #define PG8_STAGE(bufoff, gbase, voff) do { _Pragma("unroll") for (int _i = 0; _i < 2; ++_i) \
;         __builtin_amdgcn_global_load_lds((const unsigned*)((const char*)(gbase) + (voff)[_i]), (PG8_LAS unsigned*)(lds + (bufoff) + ldsw + _i * 8192), 16, 0, 0); } while (0)
; #define PG8_LDA(dst, b, h) do { _Pragma("unroll") for (int m = 0; m < 4; ++m) _Pragma("unroll") for (int k = 0; k < 2; ++k) dst[m][k] = *(const PG8_LAS bf16x8*)(lds + PG8_SA(b, h) + aoff + m * 2048 + k * 1024); } while (0)
; #define PG8_LDB(dst, b, h) do { _Pragma("unroll") for (int n = 0; n < 2; ++n) _Pragma("unroll") for (int k = 0; k < 2; ++k) dst[n][k] = *(const PG8_LAS bf16x8*)(lds + PG8_SB(b, h) + boff + n * 2048 + k * 1024); } while (0)
; #define PG8_MMA(ai, bj, At, Bt) do { __builtin_amdgcn_s_setprio(1); _Pragma("unroll") for (int m = 0; m < 4; ++m) _Pragma("unroll") for (int n = 0; n < 2; ++n) _Pragma("unroll") for (int k = 0; k < 2; ++k) \
;         acc[ai][bj][m][n] = __builtin_amdgcn_mfma_f32_16x16x32_bf16(Bt[n][k], At[m][k], acc[ai][bj][m][n], 0, 0, 0); __builtin_amdgcn_s_setprio(0); } while (0)
; #define PG8_WAIT_V(n) asm volatile("s_waitcnt vmcnt(" #n ")" ::: "memory")
; #define PG8_WAIT_L(n) asm volatile("s_waitcnt lgkmcnt(" #n ")" ::: "memory")
; #define PG8_BAR __builtin_amdgcn_s_barrier()
; #define PG8_SCHED __builtin_amdgcn_sched_barrier(0)
; template <class Epi, class Sched, bool ALIGN_EPI = false, bool SP2 = false>
; __device__ __forceinline__ void gemm_phase(PG8_LAS unsigned char* lds, const Gemm g, const Sched& S, const Epi& E) {
;     ...
;             PG8_LDB(B0, 1, 0); PG8_LDB(B1, 1, 1); PG8_SCHED; PG8_LDA(At, 1, 0); PG8_STAGE(PG8_SA(0, 1), a2 + hstep, voffA);
;             PG8_WAIT_V(8); PG8_WAIT_L(0); PG8_BAR; PG8_MMA(0, 0, At, B0); PG8_MMA(0, 1, At, B1); PG8_BAR; PG8_SCHED;
	s_add_i32 s56, 0, 0x18000
	s_add_i32 s57, 0, 0x1c000
	v_add_u32_e32 v94, s56, v203
	v_add_u32_e32 v134, s57, v203
	ds_read_b128 v[66:69], v94
	ds_read_b128 v[70:73], v94 offset:1024
	ds_read_b128 v[82:85], v94 offset:2048
	ds_read_b128 v[94:97], v94 offset:3072
	ds_read_b128 v[106:109], v134
	ds_read_b128 v[118:121], v134 offset:1024
	ds_read_b128 v[130:133], v134 offset:2048
	ds_read_b128 v[134:137], v134 offset:3072
	s_add_u32 s36, s36, 0x40000
	s_addc_u32 s37, s37, 0
	s_mov_b32 m0, s45
	v_lshl_add_u64 v[228:229], s[36:37], 0, v[182:183]
	ds_read_b128 v[162:165], v204 offset:32768
	ds_read_b128 v[166:169], v204 offset:33792
	ds_read_b128 v[188:191], v204 offset:34816
	ds_read_b128 v[192:195], v204 offset:35840
	ds_read_b128 v[196:199], v204 offset:36864
	ds_read_b128 v[206:209], v204 offset:37888
	ds_read_b128 v[210:213], v204 offset:38912
	ds_read_b128 v[214:217], v204 offset:39936
	global_load_lds_dwordx4 v[228:229], off
	v_lshl_add_u64 v[228:229], s[36:37], 0, v[172:173]
	s_mov_b32 m0, s46
	s_nop 0
	global_load_lds_dwordx4 v[228:229], off
	s_waitcnt vmcnt(8)
	s_waitcnt lgkmcnt(0)
	s_barrier
	s_waitcnt lgkmcnt(0)
	v_mfma_f32_16x16x32_bf16 v[158:161], v[66:69], v[162:165], v[158:161]
	v_mfma_f32_16x16x32_bf16 v[154:157], v[82:85], v[162:165], v[154:157]
	v_mfma_f32_16x16x32_bf16 v[142:145], v[66:69], v[188:191], v[142:145]
	v_mfma_f32_16x16x32_bf16 v[138:141], v[82:85], v[188:191], v[138:141]
	v_mfma_f32_16x16x32_bf16 v[114:117], v[66:69], v[196:199], v[114:117]
	v_mfma_f32_16x16x32_bf16 v[110:113], v[82:85], v[196:199], v[110:113]
	v_mfma_f32_16x16x32_bf16 v[90:93], v[66:69], v[210:213], v[90:93]
	v_mfma_f32_16x16x32_bf16 v[86:89], v[82:85], v[210:213], v[86:89]
	v_mfma_f32_16x16x32_bf16 v[158:161], v[70:73], v[166:169], v[158:161]
	v_mfma_f32_16x16x32_bf16 v[154:157], v[94:97], v[166:169], v[154:157]
	v_mfma_f32_16x16x32_bf16 v[142:145], v[70:73], v[192:195], v[142:145]
	v_mfma_f32_16x16x32_bf16 v[138:141], v[94:97], v[192:195], v[138:141]
	v_mfma_f32_16x16x32_bf16 v[114:117], v[70:73], v[206:209], v[114:117]
	v_mfma_f32_16x16x32_bf16 v[110:113], v[94:97], v[206:209], v[110:113]
	v_mfma_f32_16x16x32_bf16 v[90:93], v[70:73], v[214:217], v[90:93]
	v_mfma_f32_16x16x32_bf16 v[86:89], v[94:97], v[214:217], v[86:89]
	v_mfma_f32_16x16x32_bf16 v[150:153], v[106:109], v[162:165], v[150:153]
	v_mfma_f32_16x16x32_bf16 v[146:149], v[130:133], v[162:165], v[146:149]
	v_mfma_f32_16x16x32_bf16 v[126:129], v[106:109], v[188:191], v[126:129]
	v_mfma_f32_16x16x32_bf16 v[122:125], v[130:133], v[188:191], v[122:125]
	v_mfma_f32_16x16x32_bf16 v[102:105], v[106:109], v[196:199], v[102:105]
	v_mfma_f32_16x16x32_bf16 v[98:101], v[130:133], v[196:199], v[98:101]
	v_mfma_f32_16x16x32_bf16 v[78:81], v[106:109], v[210:213], v[78:81]
	v_mfma_f32_16x16x32_bf16 v[74:77], v[130:133], v[210:213], v[74:77]
	v_mfma_f32_16x16x32_bf16 v[150:153], v[118:121], v[166:169], v[150:153]
	v_mfma_f32_16x16x32_bf16 v[146:149], v[134:137], v[166:169], v[146:149]
	v_mfma_f32_16x16x32_bf16 v[126:129], v[118:121], v[192:195], v[126:129]
	v_mfma_f32_16x16x32_bf16 v[122:125], v[134:137], v[192:195], v[122:125]
	v_mfma_f32_16x16x32_bf16 v[102:105], v[118:121], v[206:209], v[102:105]
	v_mfma_f32_16x16x32_bf16 v[98:101], v[134:137], v[206:209], v[98:101]
	v_mfma_f32_16x16x32_bf16 v[78:81], v[118:121], v[214:217], v[78:81]
	v_mfma_f32_16x16x32_bf16 v[74:77], v[134:137], v[214:217], v[74:77]
	s_barrier
; #define PG8_STAGE(bufoff, gbase, voff) do { _Pragma("unroll") for (int _i = 0; _i < 2; ++_i) \
;         __builtin_amdgcn_global_load_lds((const unsigned*)((const char*)(gbase) + (voff)[_i]), (PG8_LAS unsigned*)(lds + (bufoff) + ldsw + _i * 8192), 16, 0, 0); } while (0)
; #define PG8_LDA(dst, b, h) do { _Pragma("unroll") for (int m = 0; m < 4; ++m) _Pragma("unroll") for (int k = 0; k < 2; ++k) dst[m][k] = *(const PG8_LAS bf16x8*)(lds + PG8_SA(b, h) + aoff + m * 2048 + k * 1024); } while (0)
; #define PG8_MMA(ai, bj, At, Bt) do { __builtin_amdgcn_s_setprio(1); _Pragma("unroll") for (int m = 0; m < 4; ++m) _Pragma("unroll") for (int n = 0; n < 2; ++n) _Pragma("unroll") for (int k = 0; k < 2; ++k) \
;         acc[ai][bj][m][n] = __builtin_amdgcn_mfma_f32_16x16x32_bf16(Bt[n][k], At[m][k], acc[ai][bj][m][n], 0, 0, 0); __builtin_amdgcn_s_setprio(0); } while (0)
; #define PG8_WAIT_V(n) asm volatile("s_waitcnt vmcnt(" #n ")" ::: "memory")
; #define PG8_WAIT_L(n) asm volatile("s_waitcnt lgkmcnt(" #n ")" ::: "memory")
; #define PG8_BAR __builtin_amdgcn_s_barrier()
; #define PG8_SCHED __builtin_amdgcn_sched_barrier(0)
; template <class Epi, class Sched, bool ALIGN_EPI = false, bool SP2 = false>
; __device__ __forceinline__ void gemm_phase(PG8_LAS unsigned char* lds, const Gemm g, const Sched& S, const Epi& E) {
;     ...
;         for (int t = 0; t < nt; t += 2) {
;             const bool last = (t == nt - 2);
;             const char* a1 = cA + (size_t)(t + 1) * kstep;
;             const char* a2 = last ? nA : cA + (size_t)(t + 2) * kstep; const char* b2 = last ? nB : cB + (size_t)(t + 2) * kstep;
;     ...
;             PG8_LDA(At, 1, 1); PG8_STAGE(PG8_SB(1, 0), b3, voffB); PG8_STAGE(PG8_SB(1, 1), b3 + hstep, voffB); PG8_STAGE(PG8_SA(1, 0), a3, voffA);
;             PG8_WAIT_V(8); PG8_WAIT_L(0); PG8_BAR; PG8_MMA(1, 0, At, B0); PG8_MMA(1, 1, At, B1); PG8_BAR; PG8_SCHED;
	s_add_i32 s36, s56, s42
	v_lshl_add_u64 v[200:201], v[200:201], 0, s[96:97]
	s_mov_b32 m0, s36
	ds_read_b128 v[162:165], v204 offset:49152
	ds_read_b128 v[166:169], v204 offset:50176
	ds_read_b128 v[188:191], v204 offset:51200
	ds_read_b128 v[192:195], v204 offset:52224
	ds_read_b128 v[196:199], v204 offset:53248
	ds_read_b128 v[206:209], v204 offset:54272
	ds_read_b128 v[210:213], v204 offset:55296
	ds_read_b128 v[214:217], v204 offset:56320
	global_load_lds_dwordx4 v[200:201], off
	s_add_i32 m0, s36, 0x2000
	s_add_u32 s10, s10, 0x40080
	v_lshl_add_u64 v[200:201], v[218:219], 0, s[96:97]
	s_addc_u32 s11, s11, 0
	s_add_i32 s36, s57, s42
	global_load_lds_dwordx4 v[200:201], off
	v_lshl_add_u64 v[200:201], s[10:11], 0, v[180:181]
	s_mov_b32 m0, s36
	s_nop 0
	global_load_lds_dwordx4 v[200:201], off
	v_lshl_add_u64 v[200:201], s[10:11], 0, v[170:171]
	s_add_i32 m0, s36, 0x2000
	s_nop 0
	global_load_lds_dwordx4 v[200:201], off
	v_lshl_add_u64 v[200:201], v[220:221], 0, s[96:97]
	s_mov_b32 m0, s50
	s_nop 0
	global_load_lds_dwordx4 v[200:201], off
	v_lshl_add_u64 v[200:201], v[222:223], 0, s[96:97]
	s_mov_b32 m0, s51
	s_nop 0
	global_load_lds_dwordx4 v[200:201], off
	s_waitcnt vmcnt(8)
	s_waitcnt lgkmcnt(0)
	s_barrier
	s_waitcnt lgkmcnt(0)
	v_mfma_f32_16x16x32_bf16 v[62:65], v[66:69], v[162:165], v[62:65]
	v_mfma_f32_16x16x32_bf16 v[58:61], v[82:85], v[162:165], v[58:61]
	v_mfma_f32_16x16x32_bf16 v[46:49], v[66:69], v[188:191], v[46:49]
	v_mfma_f32_16x16x32_bf16 v[42:45], v[82:85], v[188:191], v[42:45]
	v_mfma_f32_16x16x32_bf16 v[30:33], v[66:69], v[196:199], v[30:33]
	v_mfma_f32_16x16x32_bf16 v[26:29], v[82:85], v[196:199], v[26:29]
	v_mfma_f32_16x16x32_bf16 v[14:17], v[66:69], v[210:213], v[14:17]
	v_mfma_f32_16x16x32_bf16 v[10:13], v[82:85], v[210:213], v[10:13]
	v_mfma_f32_16x16x32_bf16 v[62:65], v[70:73], v[166:169], v[62:65]
	v_mfma_f32_16x16x32_bf16 v[58:61], v[94:97], v[166:169], v[58:61]
	v_mfma_f32_16x16x32_bf16 v[46:49], v[70:73], v[192:195], v[46:49]
	v_mfma_f32_16x16x32_bf16 v[42:45], v[94:97], v[192:195], v[42:45]
	v_mfma_f32_16x16x32_bf16 v[30:33], v[70:73], v[206:209], v[30:33]
	v_mfma_f32_16x16x32_bf16 v[26:29], v[94:97], v[206:209], v[26:29]
	v_mfma_f32_16x16x32_bf16 v[14:17], v[70:73], v[214:217], v[14:17]
	v_mfma_f32_16x16x32_bf16 v[10:13], v[94:97], v[214:217], v[10:13]
	v_mfma_f32_16x16x32_bf16 v[54:57], v[106:109], v[162:165], v[54:57]
	v_mfma_f32_16x16x32_bf16 v[50:53], v[130:133], v[162:165], v[50:53]
	v_mfma_f32_16x16x32_bf16 v[38:41], v[106:109], v[188:191], v[38:41]
	v_mfma_f32_16x16x32_bf16 v[34:37], v[130:133], v[188:191], v[34:37]
	v_mfma_f32_16x16x32_bf16 v[22:25], v[106:109], v[196:199], v[22:25]
	v_mfma_f32_16x16x32_bf16 v[18:21], v[130:133], v[196:199], v[18:21]
	v_mfma_f32_16x16x32_bf16 v[6:9], v[106:109], v[210:213], v[6:9]
	v_mfma_f32_16x16x32_bf16 v[2:5], v[130:133], v[210:213], v[2:5]
	v_mfma_f32_16x16x32_bf16 v[54:57], v[118:121], v[166:169], v[54:57]
	v_mfma_f32_16x16x32_bf16 v[50:53], v[134:137], v[166:169], v[50:53]
	v_mfma_f32_16x16x32_bf16 v[38:41], v[118:121], v[192:195], v[38:41]
	v_mfma_f32_16x16x32_bf16 v[34:37], v[134:137], v[192:195], v[34:37]
	v_mfma_f32_16x16x32_bf16 v[22:25], v[118:121], v[206:209], v[22:25]
	v_mfma_f32_16x16x32_bf16 v[18:21], v[134:137], v[206:209], v[18:21]
	v_mfma_f32_16x16x32_bf16 v[6:9], v[118:121], v[214:217], v[6:9]
	v_mfma_f32_16x16x32_bf16 v[2:5], v[134:137], v[214:217], v[2:5]
	s_barrier
	s_add_i32 s55, s55, 2
	s_add_u32 s8, s8, 0x100
	s_addc_u32 s9, s9, 0
	s_add_u32 s33, s33, 0x100
	s_addc_u32 s54, s54, 0
	s_cmp_gt_u32 s55, 13
	s_cbranch_scc0 .LBB0_1075
	s_and_b64 vcc, exec, s[20:21]
	s_cbranch_vccz .LBB0_1078
	s_barrier

; #define PG8_STAGE(bufoff, gbase, voff) do { _Pragma("unroll") for (int _i = 0; _i < 2; ++_i) \
;         __builtin_amdgcn_global_load_lds((const unsigned*)((const char*)(gbase) + (voff)[_i]), (PG8_LAS unsigned*)(lds + (bufoff) + ldsw + _i * 8192), 16, 0, 0); } while (0)
; #define PG8_LDA(dst, b, h) do { _Pragma("unroll") for (int m = 0; m < 4; ++m) _Pragma("unroll") for (int k = 0; k < 2; ++k) dst[m][k] = *(const PG8_LAS bf16x8*)(lds + PG8_SA(b, h) + aoff + m * 2048 + k * 1024); } while (0)
; #define PG8_MMA(ai, bj, At, Bt) do { __builtin_amdgcn_s_setprio(1); _Pragma("unroll") for (int m = 0; m < 4; ++m) _Pragma("unroll") for (int n = 0; n < 2; ++n) _Pragma("unroll") for (int k = 0; k < 2; ++k) \
;         acc[ai][bj][m][n] = __builtin_amdgcn_mfma_f32_16x16x32_bf16(Bt[n][k], At[m][k], acc[ai][bj][m][n], 0, 0, 0); __builtin_amdgcn_s_setprio(0); } while (0)
; #define PG8_WAIT_V(n) asm volatile("s_waitcnt vmcnt(" #n ")" ::: "memory")
; #define PG8_WAIT_L(n) asm volatile("s_waitcnt lgkmcnt(" #n ")" ::: "memory")
; #define PG8_BAR __builtin_amdgcn_s_barrier()
; #define PG8_SCHED __builtin_amdgcn_sched_barrier(0)
; template <class Epi, class Sched, bool ALIGN_EPI = false, bool SP2 = false>
; __device__ __forceinline__ void gemm_phase(PG8_LAS unsigned char* lds, const Gemm g, const Sched& S, const Epi& E) {
;     ...
;             PG8_WAIT_V(8); PG8_WAIT_L(0); PG8_BAR; PG8_MMA(0, 0, At, B0); PG8_MMA(0, 1, At, B1); PG8_BAR; PG8_SCHED;
;             PG8_LDA(At, 0, 1); PG8_STAGE(PG8_SB(0, 0), b2, voffB); PG8_STAGE(PG8_SB(0, 1), b2 + hstep, voffB); PG8_STAGE(PG8_SA(0, 0), a2, voffA);
;             PG8_WAIT_V(8); PG8_WAIT_L(0); PG8_BAR; PG8_MMA(1, 0, At, B0); PG8_MMA(1, 1, At, B1); PG8_BAR; PG8_SCHED;
.Lffin_noz:
	s_waitcnt vmcnt(8)
	s_waitcnt lgkmcnt(0)
	s_barrier
	s_waitcnt lgkmcnt(0)
	v_mfma_f32_16x16x32_bf16 v[158:161], v[106:109], v[162:165], v[158:161]
	v_mfma_f32_16x16x32_bf16 v[154:157], v[114:117], v[162:165], v[154:157]
	v_mfma_f32_16x16x32_bf16 v[142:145], v[106:109], v[170:173], v[142:145]
	v_mfma_f32_16x16x32_bf16 v[138:141], v[114:117], v[170:173], v[138:141]
	v_mfma_f32_16x16x32_bf16 v[94:97], v[106:109], v[196:199], v[94:97]
	v_mfma_f32_16x16x32_bf16 v[90:93], v[114:117], v[196:199], v[90:93]
	v_mfma_f32_16x16x32_bf16 v[78:81], v[106:109], v[204:207], v[78:81]
	v_mfma_f32_16x16x32_bf16 v[74:77], v[114:117], v[204:207], v[74:77]
	v_mfma_f32_16x16x32_bf16 v[158:161], v[110:113], v[166:169], v[158:161]
	v_mfma_f32_16x16x32_bf16 v[154:157], v[118:121], v[166:169], v[154:157]
	v_mfma_f32_16x16x32_bf16 v[142:145], v[110:113], v[192:195], v[142:145]
	v_mfma_f32_16x16x32_bf16 v[138:141], v[118:121], v[192:195], v[138:141]
	v_mfma_f32_16x16x32_bf16 v[94:97], v[110:113], v[200:203], v[94:97]
	v_mfma_f32_16x16x32_bf16 v[90:93], v[118:121], v[200:203], v[90:93]
	v_mfma_f32_16x16x32_bf16 v[78:81], v[110:113], v[208:211], v[78:81]
	v_mfma_f32_16x16x32_bf16 v[74:77], v[118:121], v[208:211], v[74:77]
	v_mfma_f32_16x16x32_bf16 v[150:153], v[122:125], v[162:165], v[150:153]
	v_mfma_f32_16x16x32_bf16 v[146:149], v[130:133], v[162:165], v[146:149]
	v_mfma_f32_16x16x32_bf16 v[102:105], v[122:125], v[170:173], v[102:105]
	v_mfma_f32_16x16x32_bf16 v[98:101], v[130:133], v[170:173], v[98:101]
	v_mfma_f32_16x16x32_bf16 v[86:89], v[122:125], v[196:199], v[86:89]
	v_mfma_f32_16x16x32_bf16 v[82:85], v[130:133], v[196:199], v[82:85]
	v_mfma_f32_16x16x32_bf16 v[70:73], v[122:125], v[204:207], v[70:73]
	v_mfma_f32_16x16x32_bf16 v[66:69], v[130:133], v[204:207], v[66:69]
	v_mfma_f32_16x16x32_bf16 v[150:153], v[126:129], v[166:169], v[150:153]
	v_mfma_f32_16x16x32_bf16 v[146:149], v[134:137], v[166:169], v[146:149]
	v_mfma_f32_16x16x32_bf16 v[102:105], v[126:129], v[192:195], v[102:105]
	v_mfma_f32_16x16x32_bf16 v[98:101], v[134:137], v[192:195], v[98:101]
	v_mfma_f32_16x16x32_bf16 v[86:89], v[126:129], v[200:203], v[86:89]
	v_mfma_f32_16x16x32_bf16 v[82:85], v[134:137], v[200:203], v[82:85]
	v_mfma_f32_16x16x32_bf16 v[70:73], v[126:129], v[208:211], v[70:73]
	v_mfma_f32_16x16x32_bf16 v[66:69], v[134:137], v[208:211], v[66:69]
	s_barrier
	s_add_i32 s69, s69, s52
	v_lshl_add_u64 v[212:213], s[44:45], 0, v[184:185]
	s_mov_b32 m0, s69
	ds_read_b128 v[162:165], v230 offset:16384
	ds_read_b128 v[166:169], v230 offset:17408
	ds_read_b128 v[170:173], v230 offset:18432
	ds_read_b128 v[192:195], v230 offset:19456
	ds_read_b128 v[196:199], v230 offset:20480
	ds_read_b128 v[200:203], v230 offset:21504
	ds_read_b128 v[204:207], v230 offset:22528
	ds_read_b128 v[208:211], v230 offset:23552
	global_load_lds_dwordx4 v[212:213], off
	s_add_i32 m0, s69, 0x2000
	s_add_u32 s70, s44, 0x40000
	v_lshl_add_u64 v[214:215], s[44:45], 0, v[180:181]
	s_addc_u32 s71, s45, 0
	s_add_i32 s69, s72, s52
	global_load_lds_dwordx4 v[214:215], off
	v_lshl_add_u64 v[216:217], s[70:71], 0, v[184:185]
	s_mov_b32 m0, s69
	v_lshl_add_u64 v[218:219], s[46:47], 0, v[182:183]
	global_load_lds_dwordx4 v[216:217], off
	v_lshl_add_u64 v[216:217], s[70:71], 0, v[180:181]
	s_add_i32 m0, s69, 0x2000
	s_nop 0
	global_load_lds_dwordx4 v[216:217], off
	v_lshl_add_u64 v[216:217], s[46:47], 0, v[186:187]
	s_mov_b32 m0, s53
	s_nop 0
	global_load_lds_dwordx4 v[216:217], off
	s_mov_b32 m0, s54
	s_nop 0
	global_load_lds_dwordx4 v[218:219], off
	s_cmp_lg_u32 s68, -2
	s_cbranch_scc1 .Lffin_w8
	s_cmp_lt_u32 s57, 2
	s_cbranch_scc1 .Lffin_w8
	s_waitcnt vmcnt(16)
	s_branch .Lffin_wd

; #define PG8_STAGE(bufoff, gbase, voff) do { _Pragma("unroll") for (int _i = 0; _i < 2; ++_i) \
;         __builtin_amdgcn_global_load_lds((const unsigned*)((const char*)(gbase) + (voff)[_i]), (PG8_LAS unsigned*)(lds + (bufoff) + ldsw + _i * 8192), 16, 0, 0); } while (0)
; #define PG8_LDA(dst, b, h) do { _Pragma("unroll") for (int m = 0; m < 4; ++m) _Pragma("unroll") for (int k = 0; k < 2; ++k) dst[m][k] = *(const PG8_LAS bf16x8*)(lds + PG8_SA(b, h) + aoff + m * 2048 + k * 1024); } while (0)
; #define PG8_LDB(dst, b, h) do { _Pragma("unroll") for (int n = 0; n < 2; ++n) _Pragma("unroll") for (int k = 0; k < 2; ++k) dst[n][k] = *(const PG8_LAS bf16x8*)(lds + PG8_SB(b, h) + boff + n * 2048 + k * 1024); } while (0)
; #define PG8_MMA(ai, bj, At, Bt) do { __builtin_amdgcn_s_setprio(1); _Pragma("unroll") for (int m = 0; m < 4; ++m) _Pragma("unroll") for (int n = 0; n < 2; ++n) _Pragma("unroll") for (int k = 0; k < 2; ++k) \
;         acc[ai][bj][m][n] = __builtin_amdgcn_mfma_f32_16x16x32_bf16(Bt[n][k], At[m][k], acc[ai][bj][m][n], 0, 0, 0); __builtin_amdgcn_s_setprio(0); } while (0)
; #define PG8_WAIT_V(n) asm volatile("s_waitcnt vmcnt(" #n ")" ::: "memory")
; #define PG8_WAIT_L(n) asm volatile("s_waitcnt lgkmcnt(" #n ")" ::: "memory")
; #define PG8_BAR __builtin_amdgcn_s_barrier()
; #define PG8_SCHED __builtin_amdgcn_sched_barrier(0)
; template <class Epi, class Sched, bool ALIGN_EPI = false, bool SP2 = false>
; __device__ __forceinline__ void gemm_phase(PG8_LAS unsigned char* lds, const Gemm g, const Sched& S, const Epi& E) {
;     ...
;             PG8_WAIT_V(8); PG8_WAIT_L(0); PG8_BAR; PG8_MMA(1, 0, At, B0); PG8_MMA(1, 1, At, B1); PG8_BAR; PG8_SCHED;
;             PG8_LDB(B0, 1, 0); PG8_LDB(B1, 1, 1); PG8_SCHED; PG8_LDA(At, 1, 0); PG8_STAGE(PG8_SA(0, 1), a2 + hstep, voffA);
;             PG8_WAIT_V(8); PG8_WAIT_L(0); PG8_BAR; PG8_MMA(0, 0, At, B0); PG8_MMA(0, 1, At, B1); PG8_BAR; PG8_SCHED;
.Lffin_wd:
	s_waitcnt lgkmcnt(0)
	s_barrier
	s_waitcnt lgkmcnt(0)
	v_mfma_f32_16x16x32_bf16 v[62:65], v[106:109], v[162:165], v[62:65]
	v_mfma_f32_16x16x32_bf16 v[58:61], v[114:117], v[162:165], v[58:61]
	v_mfma_f32_16x16x32_bf16 v[46:49], v[106:109], v[170:173], v[46:49]
	v_mfma_f32_16x16x32_bf16 v[42:45], v[114:117], v[170:173], v[42:45]
	v_mfma_f32_16x16x32_bf16 v[30:33], v[106:109], v[196:199], v[30:33]
	v_mfma_f32_16x16x32_bf16 v[26:29], v[114:117], v[196:199], v[26:29]
	v_mfma_f32_16x16x32_bf16 v[14:17], v[106:109], v[204:207], v[14:17]
	v_mfma_f32_16x16x32_bf16 v[10:13], v[114:117], v[204:207], v[10:13]
	v_mfma_f32_16x16x32_bf16 v[62:65], v[110:113], v[166:169], v[62:65]
	v_mfma_f32_16x16x32_bf16 v[58:61], v[118:121], v[166:169], v[58:61]
	v_mfma_f32_16x16x32_bf16 v[46:49], v[110:113], v[192:195], v[46:49]
	v_mfma_f32_16x16x32_bf16 v[42:45], v[118:121], v[192:195], v[42:45]
	v_mfma_f32_16x16x32_bf16 v[30:33], v[110:113], v[200:203], v[30:33]
	v_mfma_f32_16x16x32_bf16 v[26:29], v[118:121], v[200:203], v[26:29]
	v_mfma_f32_16x16x32_bf16 v[14:17], v[110:113], v[208:211], v[14:17]
	v_mfma_f32_16x16x32_bf16 v[10:13], v[118:121], v[208:211], v[10:13]
	v_mfma_f32_16x16x32_bf16 v[54:57], v[122:125], v[162:165], v[54:57]
	v_mfma_f32_16x16x32_bf16 v[50:53], v[130:133], v[162:165], v[50:53]
	v_mfma_f32_16x16x32_bf16 v[38:41], v[122:125], v[170:173], v[38:41]
	v_mfma_f32_16x16x32_bf16 v[34:37], v[130:133], v[170:173], v[34:37]
	v_mfma_f32_16x16x32_bf16 v[22:25], v[122:125], v[196:199], v[22:25]
	v_mfma_f32_16x16x32_bf16 v[18:21], v[130:133], v[196:199], v[18:21]
	v_mfma_f32_16x16x32_bf16 v[6:9], v[122:125], v[204:207], v[6:9]
	v_mfma_f32_16x16x32_bf16 v[2:5], v[130:133], v[204:207], v[2:5]
	v_mfma_f32_16x16x32_bf16 v[54:57], v[126:129], v[166:169], v[54:57]
	v_mfma_f32_16x16x32_bf16 v[50:53], v[134:137], v[166:169], v[50:53]
	v_mfma_f32_16x16x32_bf16 v[38:41], v[126:129], v[192:195], v[38:41]
	v_mfma_f32_16x16x32_bf16 v[34:37], v[134:137], v[192:195], v[34:37]
	v_mfma_f32_16x16x32_bf16 v[22:25], v[126:129], v[200:203], v[22:25]
	v_mfma_f32_16x16x32_bf16 v[18:21], v[134:137], v[200:203], v[18:21]
	v_mfma_f32_16x16x32_bf16 v[6:9], v[126:129], v[208:211], v[6:9]
	v_mfma_f32_16x16x32_bf16 v[2:5], v[134:137], v[208:211], v[2:5]
	s_barrier
	s_add_i32 s69, 0, 0x18000
	s_add_i32 s70, 0, 0x1c000
	v_add_u32_e32 v118, s69, v229
	v_add_u32_e32 v134, s70, v229
	ds_read_b128 v[106:109], v118
	ds_read_b128 v[110:113], v118 offset:1024
	ds_read_b128 v[114:117], v118 offset:2048
	ds_read_b128 v[118:121], v118 offset:3072
	ds_read_b128 v[122:125], v134
	ds_read_b128 v[126:129], v134 offset:1024
	ds_read_b128 v[130:133], v134 offset:2048
	ds_read_b128 v[134:137], v134 offset:3072
	s_add_u32 s46, s46, 0x40000
	s_addc_u32 s47, s47, 0
	s_mov_b32 m0, s55
	v_lshl_add_u64 v[220:221], s[46:47], 0, v[186:187]
	ds_read_b128 v[162:165], v230 offset:32768
	ds_read_b128 v[166:169], v230 offset:33792
	ds_read_b128 v[170:173], v230 offset:34816
	ds_read_b128 v[192:195], v230 offset:35840
	ds_read_b128 v[196:199], v230 offset:36864
	ds_read_b128 v[200:203], v230 offset:37888
	ds_read_b128 v[204:207], v230 offset:38912
	ds_read_b128 v[208:211], v230 offset:39936
	global_load_lds_dwordx4 v[220:221], off
	v_lshl_add_u64 v[220:221], s[46:47], 0, v[182:183]
	s_mov_b32 m0, s56
	s_nop 0
	global_load_lds_dwordx4 v[220:221], off
	s_waitcnt vmcnt(8)
	s_waitcnt lgkmcnt(0)
	s_barrier
	s_waitcnt lgkmcnt(0)
	v_mfma_f32_16x16x32_bf16 v[158:161], v[106:109], v[162:165], v[158:161]
	v_mfma_f32_16x16x32_bf16 v[154:157], v[114:117], v[162:165], v[154:157]
	v_mfma_f32_16x16x32_bf16 v[142:145], v[106:109], v[170:173], v[142:145]
	v_mfma_f32_16x16x32_bf16 v[138:141], v[114:117], v[170:173], v[138:141]
	v_mfma_f32_16x16x32_bf16 v[94:97], v[106:109], v[196:199], v[94:97]
	v_mfma_f32_16x16x32_bf16 v[90:93], v[114:117], v[196:199], v[90:93]
	v_mfma_f32_16x16x32_bf16 v[78:81], v[106:109], v[204:207], v[78:81]
	v_mfma_f32_16x16x32_bf16 v[74:77], v[114:117], v[204:207], v[74:77]
	v_mfma_f32_16x16x32_bf16 v[158:161], v[110:113], v[166:169], v[158:161]
	v_mfma_f32_16x16x32_bf16 v[154:157], v[118:121], v[166:169], v[154:157]
	v_mfma_f32_16x16x32_bf16 v[142:145], v[110:113], v[192:195], v[142:145]
	v_mfma_f32_16x16x32_bf16 v[138:141], v[118:121], v[192:195], v[138:141]
	v_mfma_f32_16x16x32_bf16 v[94:97], v[110:113], v[200:203], v[94:97]
	v_mfma_f32_16x16x32_bf16 v[90:93], v[118:121], v[200:203], v[90:93]
	v_mfma_f32_16x16x32_bf16 v[78:81], v[110:113], v[208:211], v[78:81]
	v_mfma_f32_16x16x32_bf16 v[74:77], v[118:121], v[208:211], v[74:77]
	v_mfma_f32_16x16x32_bf16 v[150:153], v[122:125], v[162:165], v[150:153]
	v_mfma_f32_16x16x32_bf16 v[146:149], v[130:133], v[162:165], v[146:149]
	v_mfma_f32_16x16x32_bf16 v[102:105], v[122:125], v[170:173], v[102:105]
	v_mfma_f32_16x16x32_bf16 v[98:101], v[130:133], v[170:173], v[98:101]
	v_mfma_f32_16x16x32_bf16 v[86:89], v[122:125], v[196:199], v[86:89]
	v_mfma_f32_16x16x32_bf16 v[82:85], v[130:133], v[196:199], v[82:85]
	v_mfma_f32_16x16x32_bf16 v[70:73], v[122:125], v[204:207], v[70:73]
	v_mfma_f32_16x16x32_bf16 v[66:69], v[130:133], v[204:207], v[66:69]
	v_mfma_f32_16x16x32_bf16 v[150:153], v[126:129], v[166:169], v[150:153]
	v_mfma_f32_16x16x32_bf16 v[146:149], v[134:137], v[166:169], v[146:149]
	v_mfma_f32_16x16x32_bf16 v[102:105], v[126:129], v[192:195], v[102:105]
	v_mfma_f32_16x16x32_bf16 v[98:101], v[134:137], v[192:195], v[98:101]
	v_mfma_f32_16x16x32_bf16 v[86:89], v[126:129], v[200:203], v[86:89]
	v_mfma_f32_16x16x32_bf16 v[82:85], v[134:137], v[200:203], v[82:85]
	v_mfma_f32_16x16x32_bf16 v[70:73], v[126:129], v[208:211], v[70:73]
	v_mfma_f32_16x16x32_bf16 v[66:69], v[134:137], v[208:211], v[66:69]
	s_barrier
; #define PG8_STAGE(bufoff, gbase, voff) do { _Pragma("unroll") for (int _i = 0; _i < 2; ++_i) \
;         __builtin_amdgcn_global_load_lds((const unsigned*)((const char*)(gbase) + (voff)[_i]), (PG8_LAS unsigned*)(lds + (bufoff) + ldsw + _i * 8192), 16, 0, 0); } while (0)
; #define PG8_LDA(dst, b, h) do { _Pragma("unroll") for (int m = 0; m < 4; ++m) _Pragma("unroll") for (int k = 0; k < 2; ++k) dst[m][k] = *(const PG8_LAS bf16x8*)(lds + PG8_SA(b, h) + aoff + m * 2048 + k * 1024); } while (0)
; #define PG8_MMA(ai, bj, At, Bt) do { __builtin_amdgcn_s_setprio(1); _Pragma("unroll") for (int m = 0; m < 4; ++m) _Pragma("unroll") for (int n = 0; n < 2; ++n) _Pragma("unroll") for (int k = 0; k < 2; ++k) \
;         acc[ai][bj][m][n] = __builtin_amdgcn_mfma_f32_16x16x32_bf16(Bt[n][k], At[m][k], acc[ai][bj][m][n], 0, 0, 0); __builtin_amdgcn_s_setprio(0); } while (0)
; #define PG8_WAIT_V(n) asm volatile("s_waitcnt vmcnt(" #n ")" ::: "memory")
; #define PG8_WAIT_L(n) asm volatile("s_waitcnt lgkmcnt(" #n ")" ::: "memory")
; #define PG8_BAR __builtin_amdgcn_s_barrier()
; #define PG8_SCHED __builtin_amdgcn_sched_barrier(0)
; template <class Epi, class Sched, bool ALIGN_EPI = false, bool SP2 = false>
; __device__ __forceinline__ void gemm_phase(PG8_LAS unsigned char* lds, const Gemm g, const Sched& S, const Epi& E) {
;     ...
;         for (int t = 0; t < nt; t += 2) {
;             const bool last = (t == nt - 2);
;             const char* a1 = cA + (size_t)(t + 1) * kstep;
;             const char* a2 = last ? nA : cA + (size_t)(t + 2) * kstep; const char* b2 = last ? nB : cB + (size_t)(t + 2) * kstep;
;     ...
;             PG8_LDA(At, 1, 1); PG8_STAGE(PG8_SB(1, 0), b3, voffB); PG8_STAGE(PG8_SB(1, 1), b3 + hstep, voffB); PG8_STAGE(PG8_SA(1, 0), a3, voffA);
;             PG8_WAIT_V(8); PG8_WAIT_L(0); PG8_BAR; PG8_MMA(1, 0, At, B0); PG8_MMA(1, 1, At, B1); PG8_BAR; PG8_SCHED;
	s_add_i32 s46, s69, s52
	v_lshl_add_u64 v[212:213], v[212:213], 0, s[96:97]
	s_mov_b32 m0, s46
	ds_read_b128 v[162:165], v230 offset:49152
	ds_read_b128 v[166:169], v230 offset:50176
	ds_read_b128 v[170:173], v230 offset:51200
	ds_read_b128 v[192:195], v230 offset:52224
	ds_read_b128 v[196:199], v230 offset:53248
	ds_read_b128 v[200:203], v230 offset:54272
	ds_read_b128 v[204:207], v230 offset:55296
	ds_read_b128 v[208:211], v230 offset:56320
	global_load_lds_dwordx4 v[212:213], off
	s_add_i32 m0, s46, 0x2000
	s_add_u32 s44, s44, 0x40080
	v_lshl_add_u64 v[212:213], v[214:215], 0, s[96:97]
	s_addc_u32 s45, s45, 0
	s_add_i32 s46, s70, s52
	global_load_lds_dwordx4 v[212:213], off
	v_lshl_add_u64 v[212:213], s[44:45], 0, v[184:185]
	s_mov_b32 m0, s46
	s_nop 0
	global_load_lds_dwordx4 v[212:213], off
	v_lshl_add_u64 v[212:213], s[44:45], 0, v[180:181]
	s_add_i32 m0, s46, 0x2000
	s_nop 0
	global_load_lds_dwordx4 v[212:213], off
	v_lshl_add_u64 v[212:213], v[216:217], 0, s[96:97]
	s_mov_b32 m0, s60
	s_nop 0
	global_load_lds_dwordx4 v[212:213], off
	v_lshl_add_u64 v[212:213], v[218:219], 0, s[96:97]
	s_mov_b32 m0, s61
	s_nop 0
	global_load_lds_dwordx4 v[212:213], off
	s_waitcnt vmcnt(8)
	s_waitcnt lgkmcnt(0)
	s_barrier
	s_waitcnt lgkmcnt(0)
	v_mfma_f32_16x16x32_bf16 v[62:65], v[106:109], v[162:165], v[62:65]
	v_mfma_f32_16x16x32_bf16 v[58:61], v[114:117], v[162:165], v[58:61]
	v_mfma_f32_16x16x32_bf16 v[46:49], v[106:109], v[170:173], v[46:49]
	v_mfma_f32_16x16x32_bf16 v[42:45], v[114:117], v[170:173], v[42:45]
	v_mfma_f32_16x16x32_bf16 v[30:33], v[106:109], v[196:199], v[30:33]
	v_mfma_f32_16x16x32_bf16 v[26:29], v[114:117], v[196:199], v[26:29]
	v_mfma_f32_16x16x32_bf16 v[14:17], v[106:109], v[204:207], v[14:17]
	v_mfma_f32_16x16x32_bf16 v[10:13], v[114:117], v[204:207], v[10:13]
	v_mfma_f32_16x16x32_bf16 v[62:65], v[110:113], v[166:169], v[62:65]
	v_mfma_f32_16x16x32_bf16 v[58:61], v[118:121], v[166:169], v[58:61]
	v_mfma_f32_16x16x32_bf16 v[46:49], v[110:113], v[192:195], v[46:49]
	v_mfma_f32_16x16x32_bf16 v[42:45], v[118:121], v[192:195], v[42:45]
	v_mfma_f32_16x16x32_bf16 v[30:33], v[110:113], v[200:203], v[30:33]
	v_mfma_f32_16x16x32_bf16 v[26:29], v[118:121], v[200:203], v[26:29]
	v_mfma_f32_16x16x32_bf16 v[14:17], v[110:113], v[208:211], v[14:17]
	v_mfma_f32_16x16x32_bf16 v[10:13], v[118:121], v[208:211], v[10:13]
	v_mfma_f32_16x16x32_bf16 v[54:57], v[122:125], v[162:165], v[54:57]
	v_mfma_f32_16x16x32_bf16 v[50:53], v[130:133], v[162:165], v[50:53]
	v_mfma_f32_16x16x32_bf16 v[38:41], v[122:125], v[170:173], v[38:41]
	v_mfma_f32_16x16x32_bf16 v[34:37], v[130:133], v[170:173], v[34:37]
	v_mfma_f32_16x16x32_bf16 v[22:25], v[122:125], v[196:199], v[22:25]
	v_mfma_f32_16x16x32_bf16 v[18:21], v[130:133], v[196:199], v[18:21]
	v_mfma_f32_16x16x32_bf16 v[6:9], v[122:125], v[204:207], v[6:9]
	v_mfma_f32_16x16x32_bf16 v[2:5], v[130:133], v[204:207], v[2:5]
	v_mfma_f32_16x16x32_bf16 v[54:57], v[126:129], v[166:169], v[54:57]
	v_mfma_f32_16x16x32_bf16 v[50:53], v[134:137], v[166:169], v[50:53]
	v_mfma_f32_16x16x32_bf16 v[38:41], v[126:129], v[192:195], v[38:41]
	v_mfma_f32_16x16x32_bf16 v[34:37], v[134:137], v[192:195], v[34:37]
	v_mfma_f32_16x16x32_bf16 v[22:25], v[126:129], v[200:203], v[22:25]
	v_mfma_f32_16x16x32_bf16 v[18:21], v[134:137], v[200:203], v[18:21]
	v_mfma_f32_16x16x32_bf16 v[6:9], v[126:129], v[208:211], v[6:9]
	v_mfma_f32_16x16x32_bf16 v[2:5], v[134:137], v[208:211], v[2:5]
	s_barrier
	s_add_i32 s68, s68, 2
	s_add_u32 s8, s8, 0x100
	s_addc_u32 s9, s9, 0
	s_add_u32 s66, s66, 0x100
	s_addc_u32 s67, s67, 0
	s_cmp_gt_u32 s68, 13
	s_cbranch_scc0 .LBB0_1247
	s_and_b64 vcc, exec, s[24:25]
	s_cbranch_vccz .LBB0_1250
	s_barrier

; #define PG8_STAGE(bufoff, gbase, voff) do { _Pragma("unroll") for (int _i = 0; _i < 2; ++_i) \
;         __builtin_amdgcn_global_load_lds((const unsigned*)((const char*)(gbase) + (voff)[_i]), (PG8_LAS unsigned*)(lds + (bufoff) + ldsw + _i * 8192), 16, 0, 0); } while (0)
; #define PG8_LDA(dst, b, h) do { _Pragma("unroll") for (int m = 0; m < 4; ++m) _Pragma("unroll") for (int k = 0; k < 2; ++k) dst[m][k] = *(const PG8_LAS bf16x8*)(lds + PG8_SA(b, h) + aoff + m * 2048 + k * 1024); } while (0)
; #define PG8_MMA(ai, bj, At, Bt) do { __builtin_amdgcn_s_setprio(1); _Pragma("unroll") for (int m = 0; m < 4; ++m) _Pragma("unroll") for (int n = 0; n < 2; ++n) _Pragma("unroll") for (int k = 0; k < 2; ++k) \
;         acc[ai][bj][m][n] = __builtin_amdgcn_mfma_f32_16x16x32_bf16(Bt[n][k], At[m][k], acc[ai][bj][m][n], 0, 0, 0); __builtin_amdgcn_s_setprio(0); } while (0)
; #define PG8_WAIT_V(n) asm volatile("s_waitcnt vmcnt(" #n ")" ::: "memory")
; #define PG8_WAIT_L(n) asm volatile("s_waitcnt lgkmcnt(" #n ")" ::: "memory")
; #define PG8_BAR __builtin_amdgcn_s_barrier()
; #define PG8_SCHED __builtin_amdgcn_sched_barrier(0)
; template <class Epi, class Sched, bool ALIGN_EPI = false, bool SP2 = false>
; __device__ __forceinline__ void gemm_phase(PG8_LAS unsigned char* lds, const Gemm g, const Sched& S, const Epi& E) {
;     ...
;             PG8_WAIT_V(8); PG8_WAIT_L(0); PG8_BAR; PG8_MMA(0, 0, At, B0); PG8_MMA(0, 1, At, B1); PG8_BAR; PG8_SCHED;
;             PG8_LDA(At, 0, 1); PG8_STAGE(PG8_SB(0, 0), b2, voffB); PG8_STAGE(PG8_SB(0, 1), b2 + hstep, voffB); PG8_STAGE(PG8_SA(0, 0), a2, voffA);
;             PG8_WAIT_V(8); PG8_WAIT_L(0); PG8_BAR; PG8_MMA(1, 0, At, B0); PG8_MMA(1, 1, At, B1); PG8_BAR; PG8_SCHED;
.Lffout_noz:
	s_waitcnt vmcnt(8)
	s_waitcnt lgkmcnt(0)
	s_barrier
	s_waitcnt lgkmcnt(0)
	v_mfma_f32_16x16x32_bf16 v[142:145], v[114:117], v[180:183], v[142:145]
	v_mfma_f32_16x16x32_bf16 v[138:141], v[122:125], v[180:183], v[138:141]
	v_mfma_f32_16x16x32_bf16 v[110:113], v[114:117], v[192:195], v[110:113]
	v_mfma_f32_16x16x32_bf16 v[106:109], v[122:125], v[192:195], v[106:109]
	v_mfma_f32_16x16x32_bf16 v[94:97], v[114:117], v[200:203], v[94:97]
	v_mfma_f32_16x16x32_bf16 v[90:93], v[122:125], v[200:203], v[90:93]
	v_mfma_f32_16x16x32_bf16 v[78:81], v[114:117], v[208:211], v[78:81]
	v_mfma_f32_16x16x32_bf16 v[74:77], v[122:125], v[208:211], v[74:77]
	v_mfma_f32_16x16x32_bf16 v[142:145], v[118:121], v[188:191], v[142:145]
	v_mfma_f32_16x16x32_bf16 v[138:141], v[134:137], v[188:191], v[138:141]
	v_mfma_f32_16x16x32_bf16 v[110:113], v[118:121], v[196:199], v[110:113]
	v_mfma_f32_16x16x32_bf16 v[106:109], v[134:137], v[196:199], v[106:109]
	v_mfma_f32_16x16x32_bf16 v[94:97], v[118:121], v[204:207], v[94:97]
	v_mfma_f32_16x16x32_bf16 v[90:93], v[134:137], v[204:207], v[90:93]
	v_mfma_f32_16x16x32_bf16 v[78:81], v[118:121], v[212:215], v[78:81]
	v_mfma_f32_16x16x32_bf16 v[74:77], v[134:137], v[212:215], v[74:77]
	v_mfma_f32_16x16x32_bf16 v[130:133], v[146:149], v[180:183], v[130:133]
	v_mfma_f32_16x16x32_bf16 v[126:129], v[166:169], v[180:183], v[126:129]
	v_mfma_f32_16x16x32_bf16 v[102:105], v[146:149], v[192:195], v[102:105]
	v_mfma_f32_16x16x32_bf16 v[98:101], v[166:169], v[192:195], v[98:101]
	v_mfma_f32_16x16x32_bf16 v[86:89], v[146:149], v[200:203], v[86:89]
	v_mfma_f32_16x16x32_bf16 v[82:85], v[166:169], v[200:203], v[82:85]
	v_mfma_f32_16x16x32_bf16 v[70:73], v[146:149], v[208:211], v[70:73]
	v_mfma_f32_16x16x32_bf16 v[66:69], v[166:169], v[208:211], v[66:69]
	v_mfma_f32_16x16x32_bf16 v[130:133], v[150:153], v[188:191], v[130:133]
	v_mfma_f32_16x16x32_bf16 v[126:129], v[170:173], v[188:191], v[126:129]
	v_mfma_f32_16x16x32_bf16 v[102:105], v[150:153], v[196:199], v[102:105]
	v_mfma_f32_16x16x32_bf16 v[98:101], v[170:173], v[196:199], v[98:101]
	v_mfma_f32_16x16x32_bf16 v[86:89], v[150:153], v[204:207], v[86:89]
	v_mfma_f32_16x16x32_bf16 v[82:85], v[170:173], v[204:207], v[82:85]
	v_mfma_f32_16x16x32_bf16 v[70:73], v[150:153], v[212:215], v[70:73]
	v_mfma_f32_16x16x32_bf16 v[66:69], v[170:173], v[212:215], v[66:69]
	s_barrier
	s_add_i32 s22, s51, s34
	v_lshl_add_u64 v[216:217], s[24:25], 0, v[158:159]
	s_mov_b32 m0, s22
	ds_read_b128 v[180:183], v186 offset:16384
	ds_read_b128 v[188:191], v186 offset:17408
	ds_read_b128 v[192:195], v186 offset:18432
	ds_read_b128 v[196:199], v186 offset:19456
	ds_read_b128 v[200:203], v186 offset:20480
	ds_read_b128 v[204:207], v186 offset:21504
	ds_read_b128 v[208:211], v186 offset:22528
	ds_read_b128 v[212:215], v186 offset:23552
	global_load_lds_dwordx4 v[216:217], off
	s_add_i32 m0, s22, 0x2000
	s_add_u32 s22, s24, 0xb0000
	v_lshl_add_u64 v[218:219], s[24:25], 0, v[154:155]
	s_addc_u32 s23, s25, 0
	s_add_i32 s51, s52, s34
	global_load_lds_dwordx4 v[218:219], off
	v_lshl_add_u64 v[220:221], s[22:23], 0, v[158:159]
	s_mov_b32 m0, s51
	v_lshl_add_u64 v[222:223], s[26:27], 0, v[156:157]
	global_load_lds_dwordx4 v[220:221], off
	v_lshl_add_u64 v[220:221], s[22:23], 0, v[154:155]
	s_add_i32 m0, s51, 0x2000
	s_nop 0
	global_load_lds_dwordx4 v[220:221], off
	v_lshl_add_u64 v[220:221], s[26:27], 0, v[160:161]
	s_mov_b32 m0, s35
	s_nop 0
	global_load_lds_dwordx4 v[220:221], off
	s_mov_b32 m0, s36
	s_nop 0
	global_load_lds_dwordx4 v[222:223], off
	s_waitcnt vmcnt(8)
	s_waitcnt lgkmcnt(0)
	s_barrier
	s_waitcnt lgkmcnt(0)
	v_mfma_f32_16x16x32_bf16 v[62:65], v[114:117], v[180:183], v[62:65]
	v_mfma_f32_16x16x32_bf16 v[58:61], v[122:125], v[180:183], v[58:61]
	v_mfma_f32_16x16x32_bf16 v[46:49], v[114:117], v[192:195], v[46:49]
	v_mfma_f32_16x16x32_bf16 v[42:45], v[122:125], v[192:195], v[42:45]
	v_mfma_f32_16x16x32_bf16 v[30:33], v[114:117], v[200:203], v[30:33]
	v_mfma_f32_16x16x32_bf16 v[26:29], v[122:125], v[200:203], v[26:29]
	v_mfma_f32_16x16x32_bf16 v[14:17], v[114:117], v[208:211], v[14:17]
	v_mfma_f32_16x16x32_bf16 v[10:13], v[122:125], v[208:211], v[10:13]
	v_mfma_f32_16x16x32_bf16 v[62:65], v[118:121], v[188:191], v[62:65]
	v_mfma_f32_16x16x32_bf16 v[58:61], v[134:137], v[188:191], v[58:61]
	v_mfma_f32_16x16x32_bf16 v[46:49], v[118:121], v[196:199], v[46:49]
	v_mfma_f32_16x16x32_bf16 v[42:45], v[134:137], v[196:199], v[42:45]
	v_mfma_f32_16x16x32_bf16 v[30:33], v[118:121], v[204:207], v[30:33]
	v_mfma_f32_16x16x32_bf16 v[26:29], v[134:137], v[204:207], v[26:29]
	v_mfma_f32_16x16x32_bf16 v[14:17], v[118:121], v[212:215], v[14:17]
	v_mfma_f32_16x16x32_bf16 v[10:13], v[134:137], v[212:215], v[10:13]
	v_mfma_f32_16x16x32_bf16 v[54:57], v[146:149], v[180:183], v[54:57]
	v_mfma_f32_16x16x32_bf16 v[50:53], v[166:169], v[180:183], v[50:53]
	v_mfma_f32_16x16x32_bf16 v[38:41], v[146:149], v[192:195], v[38:41]
	v_mfma_f32_16x16x32_bf16 v[34:37], v[166:169], v[192:195], v[34:37]
	v_mfma_f32_16x16x32_bf16 v[22:25], v[146:149], v[200:203], v[22:25]
	v_mfma_f32_16x16x32_bf16 v[18:21], v[166:169], v[200:203], v[18:21]
	v_mfma_f32_16x16x32_bf16 v[6:9], v[146:149], v[208:211], v[6:9]
	v_mfma_f32_16x16x32_bf16 v[2:5], v[166:169], v[208:211], v[2:5]
	v_mfma_f32_16x16x32_bf16 v[54:57], v[150:153], v[188:191], v[54:57]
	v_mfma_f32_16x16x32_bf16 v[50:53], v[170:173], v[188:191], v[50:53]
	v_mfma_f32_16x16x32_bf16 v[38:41], v[150:153], v[196:199], v[38:41]
	v_mfma_f32_16x16x32_bf16 v[34:37], v[170:173], v[196:199], v[34:37]
	v_mfma_f32_16x16x32_bf16 v[22:25], v[150:153], v[204:207], v[22:25]
	v_mfma_f32_16x16x32_bf16 v[18:21], v[170:173], v[204:207], v[18:21]
	v_mfma_f32_16x16x32_bf16 v[6:9], v[150:153], v[212:215], v[6:9]
	v_mfma_f32_16x16x32_bf16 v[2:5], v[170:173], v[212:215], v[2:5]
	s_barrier
; #define PG8_STAGE(bufoff, gbase, voff) do { _Pragma("unroll") for (int _i = 0; _i < 2; ++_i) \
;         __builtin_amdgcn_global_load_lds((const unsigned*)((const char*)(gbase) + (voff)[_i]), (PG8_LAS unsigned*)(lds + (bufoff) + ldsw + _i * 8192), 16, 0, 0); } while (0)
; #define PG8_LDA(dst, b, h) do { _Pragma("unroll") for (int m = 0; m < 4; ++m) _Pragma("unroll") for (int k = 0; k < 2; ++k) dst[m][k] = *(const PG8_LAS bf16x8*)(lds + PG8_SA(b, h) + aoff + m * 2048 + k * 1024); } while (0)
; #define PG8_LDB(dst, b, h) do { _Pragma("unroll") for (int n = 0; n < 2; ++n) _Pragma("unroll") for (int k = 0; k < 2; ++k) dst[n][k] = *(const PG8_LAS bf16x8*)(lds + PG8_SB(b, h) + boff + n * 2048 + k * 1024); } while (0)
; #define PG8_MMA(ai, bj, At, Bt) do { __builtin_amdgcn_s_setprio(1); _Pragma("unroll") for (int m = 0; m < 4; ++m) _Pragma("unroll") for (int n = 0; n < 2; ++n) _Pragma("unroll") for (int k = 0; k < 2; ++k) \
;         acc[ai][bj][m][n] = __builtin_amdgcn_mfma_f32_16x16x32_bf16(Bt[n][k], At[m][k], acc[ai][bj][m][n], 0, 0, 0); __builtin_amdgcn_s_setprio(0); } while (0)
; #define PG8_WAIT_V(n) asm volatile("s_waitcnt vmcnt(" #n ")" ::: "memory")
; #define PG8_WAIT_L(n) asm volatile("s_waitcnt lgkmcnt(" #n ")" ::: "memory")
; #define PG8_BAR __builtin_amdgcn_s_barrier()
; #define PG8_SCHED __builtin_amdgcn_sched_barrier(0)
; template <class Epi, class Sched, bool ALIGN_EPI = false, bool SP2 = false>
; __device__ __forceinline__ void gemm_phase(PG8_LAS unsigned char* lds, const Gemm g, const Sched& S, const Epi& E) {
;     ...
;             PG8_LDB(B0, 1, 0); PG8_LDB(B1, 1, 1); PG8_SCHED; PG8_LDA(At, 1, 0); PG8_STAGE(PG8_SA(0, 1), a2 + hstep, voffA);
;             PG8_WAIT_V(8); PG8_WAIT_L(0); PG8_BAR; PG8_MMA(0, 0, At, B0); PG8_MMA(0, 1, At, B1); PG8_BAR; PG8_SCHED;
	s_add_i32 s51, 0, 0x18000
	s_add_i32 s52, 0, 0x1c000
	v_add_u32_e32 v134, s51, v185
	v_add_u32_e32 v170, s52, v185
	ds_read_b128 v[114:117], v134
	ds_read_b128 v[118:121], v134 offset:1024
	ds_read_b128 v[122:125], v134 offset:2048
	ds_read_b128 v[134:137], v134 offset:3072
	ds_read_b128 v[146:149], v170
	ds_read_b128 v[150:153], v170 offset:1024
	ds_read_b128 v[166:169], v170 offset:2048
	ds_read_b128 v[170:173], v170 offset:3072
	s_add_u32 s22, s26, 0xb0000
	s_addc_u32 s23, s27, 0
	s_mov_b32 m0, s37
	v_lshl_add_u64 v[228:229], s[22:23], 0, v[160:161]
	ds_read_b128 v[180:183], v186 offset:32768
	ds_read_b128 v[188:191], v186 offset:33792
	ds_read_b128 v[192:195], v186 offset:34816
	ds_read_b128 v[196:199], v186 offset:35840
	ds_read_b128 v[200:203], v186 offset:36864
	ds_read_b128 v[204:207], v186 offset:37888
	ds_read_b128 v[208:211], v186 offset:38912
	ds_read_b128 v[212:215], v186 offset:39936
	global_load_lds_dwordx4 v[228:229], off
	v_lshl_add_u64 v[228:229], s[22:23], 0, v[156:157]
	s_mov_b32 m0, s38
	s_nop 0
	global_load_lds_dwordx4 v[228:229], off
	s_waitcnt vmcnt(8)
	s_waitcnt lgkmcnt(0)
	s_barrier
	s_waitcnt lgkmcnt(0)
	v_mfma_f32_16x16x32_bf16 v[142:145], v[114:117], v[180:183], v[142:145]
	v_mfma_f32_16x16x32_bf16 v[138:141], v[122:125], v[180:183], v[138:141]
	v_mfma_f32_16x16x32_bf16 v[110:113], v[114:117], v[192:195], v[110:113]
	v_mfma_f32_16x16x32_bf16 v[106:109], v[122:125], v[192:195], v[106:109]
	v_mfma_f32_16x16x32_bf16 v[94:97], v[114:117], v[200:203], v[94:97]
	v_mfma_f32_16x16x32_bf16 v[90:93], v[122:125], v[200:203], v[90:93]
	v_mfma_f32_16x16x32_bf16 v[78:81], v[114:117], v[208:211], v[78:81]
	v_mfma_f32_16x16x32_bf16 v[74:77], v[122:125], v[208:211], v[74:77]
	v_mfma_f32_16x16x32_bf16 v[142:145], v[118:121], v[188:191], v[142:145]
	v_mfma_f32_16x16x32_bf16 v[138:141], v[134:137], v[188:191], v[138:141]
	v_mfma_f32_16x16x32_bf16 v[110:113], v[118:121], v[196:199], v[110:113]
	v_mfma_f32_16x16x32_bf16 v[106:109], v[134:137], v[196:199], v[106:109]
	v_mfma_f32_16x16x32_bf16 v[94:97], v[118:121], v[204:207], v[94:97]
	v_mfma_f32_16x16x32_bf16 v[90:93], v[134:137], v[204:207], v[90:93]
	v_mfma_f32_16x16x32_bf16 v[78:81], v[118:121], v[212:215], v[78:81]
	v_mfma_f32_16x16x32_bf16 v[74:77], v[134:137], v[212:215], v[74:77]
	v_mfma_f32_16x16x32_bf16 v[130:133], v[146:149], v[180:183], v[130:133]
	v_mfma_f32_16x16x32_bf16 v[126:129], v[166:169], v[180:183], v[126:129]
	v_mfma_f32_16x16x32_bf16 v[102:105], v[146:149], v[192:195], v[102:105]
	v_mfma_f32_16x16x32_bf16 v[98:101], v[166:169], v[192:195], v[98:101]
	v_mfma_f32_16x16x32_bf16 v[86:89], v[146:149], v[200:203], v[86:89]
	v_mfma_f32_16x16x32_bf16 v[82:85], v[166:169], v[200:203], v[82:85]
	v_mfma_f32_16x16x32_bf16 v[70:73], v[146:149], v[208:211], v[70:73]
	v_mfma_f32_16x16x32_bf16 v[66:69], v[166:169], v[208:211], v[66:69]
	v_mfma_f32_16x16x32_bf16 v[130:133], v[150:153], v[188:191], v[130:133]
	v_mfma_f32_16x16x32_bf16 v[126:129], v[170:173], v[188:191], v[126:129]
	v_mfma_f32_16x16x32_bf16 v[102:105], v[150:153], v[196:199], v[102:105]
	v_mfma_f32_16x16x32_bf16 v[98:101], v[170:173], v[196:199], v[98:101]
	v_mfma_f32_16x16x32_bf16 v[86:89], v[150:153], v[204:207], v[86:89]
	v_mfma_f32_16x16x32_bf16 v[82:85], v[170:173], v[204:207], v[82:85]
	v_mfma_f32_16x16x32_bf16 v[70:73], v[150:153], v[212:215], v[70:73]
	v_mfma_f32_16x16x32_bf16 v[66:69], v[170:173], v[212:215], v[66:69]
	s_barrier
; #define PG8_STAGE(bufoff, gbase, voff) do { _Pragma("unroll") for (int _i = 0; _i < 2; ++_i) \
;         __builtin_amdgcn_global_load_lds((const unsigned*)((const char*)(gbase) + (voff)[_i]), (PG8_LAS unsigned*)(lds + (bufoff) + ldsw + _i * 8192), 16, 0, 0); } while (0)
; #define PG8_LDA(dst, b, h) do { _Pragma("unroll") for (int m = 0; m < 4; ++m) _Pragma("unroll") for (int k = 0; k < 2; ++k) dst[m][k] = *(const PG8_LAS bf16x8*)(lds + PG8_SA(b, h) + aoff + m * 2048 + k * 1024); } while (0)
; #define PG8_MMA(ai, bj, At, Bt) do { __builtin_amdgcn_s_setprio(1); _Pragma("unroll") for (int m = 0; m < 4; ++m) _Pragma("unroll") for (int n = 0; n < 2; ++n) _Pragma("unroll") for (int k = 0; k < 2; ++k) \
;         acc[ai][bj][m][n] = __builtin_amdgcn_mfma_f32_16x16x32_bf16(Bt[n][k], At[m][k], acc[ai][bj][m][n], 0, 0, 0); __builtin_amdgcn_s_setprio(0); } while (0)
; #define PG8_WAIT_V(n) asm volatile("s_waitcnt vmcnt(" #n ")" ::: "memory")
; #define PG8_WAIT_L(n) asm volatile("s_waitcnt lgkmcnt(" #n ")" ::: "memory")
; #define PG8_BAR __builtin_amdgcn_s_barrier()
; #define PG8_SCHED __builtin_amdgcn_sched_barrier(0)
; template <class Epi, class Sched, bool ALIGN_EPI = false, bool SP2 = false>
; __device__ __forceinline__ void gemm_phase(PG8_LAS unsigned char* lds, const Gemm g, const Sched& S, const Epi& E) {
;     ...
;         for (int t = 0; t < nt; t += 2) {
;             const bool last = (t == nt - 2);
;             const char* a1 = cA + (size_t)(t + 1) * kstep;
;             const char* a2 = last ? nA : cA + (size_t)(t + 2) * kstep; const char* b2 = last ? nB : cB + (size_t)(t + 2) * kstep;
;     ...
;             PG8_LDA(At, 1, 1); PG8_STAGE(PG8_SB(1, 0), b3, voffB); PG8_STAGE(PG8_SB(1, 1), b3 + hstep, voffB); PG8_STAGE(PG8_SA(1, 0), a3, voffA);
;             PG8_WAIT_V(8); PG8_WAIT_L(0); PG8_BAR; PG8_MMA(1, 0, At, B0); PG8_MMA(1, 1, At, B1); PG8_BAR; PG8_SCHED;
	s_add_i32 s22, s51, s34
	v_lshl_add_u64 v[216:217], v[216:217], 0, s[96:97]
	s_mov_b32 m0, s22
	ds_read_b128 v[180:183], v186 offset:49152
	ds_read_b128 v[188:191], v186 offset:50176
	ds_read_b128 v[192:195], v186 offset:51200
	ds_read_b128 v[196:199], v186 offset:52224
	ds_read_b128 v[200:203], v186 offset:53248
	ds_read_b128 v[204:207], v186 offset:54272
	ds_read_b128 v[208:211], v186 offset:55296
	ds_read_b128 v[212:215], v186 offset:56320
	global_load_lds_dwordx4 v[216:217], off
	s_add_i32 m0, s22, 0x2000
	s_add_u32 s22, s24, 0xb0080
	v_lshl_add_u64 v[216:217], v[218:219], 0, s[96:97]
	s_addc_u32 s23, s25, 0
	s_add_i32 s24, s52, s34
	global_load_lds_dwordx4 v[216:217], off
	v_lshl_add_u64 v[216:217], s[22:23], 0, v[158:159]
	s_mov_b32 m0, s24
	s_nop 0
	global_load_lds_dwordx4 v[216:217], off
	v_lshl_add_u64 v[216:217], s[22:23], 0, v[154:155]
	s_add_i32 m0, s24, 0x2000
	s_nop 0
	global_load_lds_dwordx4 v[216:217], off
	v_lshl_add_u64 v[216:217], v[220:221], 0, s[96:97]
	s_mov_b32 m0, s41
	s_nop 0
	global_load_lds_dwordx4 v[216:217], off
	v_lshl_add_u64 v[216:217], v[222:223], 0, s[96:97]
	s_mov_b32 m0, s42
	s_nop 0
	global_load_lds_dwordx4 v[216:217], off
	s_waitcnt vmcnt(8)
	s_waitcnt lgkmcnt(0)
	s_barrier
	s_waitcnt lgkmcnt(0)
	v_mfma_f32_16x16x32_bf16 v[62:65], v[114:117], v[180:183], v[62:65]
	v_mfma_f32_16x16x32_bf16 v[58:61], v[122:125], v[180:183], v[58:61]
	v_mfma_f32_16x16x32_bf16 v[46:49], v[114:117], v[192:195], v[46:49]
	v_mfma_f32_16x16x32_bf16 v[42:45], v[122:125], v[192:195], v[42:45]
	v_mfma_f32_16x16x32_bf16 v[30:33], v[114:117], v[200:203], v[30:33]
	v_mfma_f32_16x16x32_bf16 v[26:29], v[122:125], v[200:203], v[26:29]
	v_mfma_f32_16x16x32_bf16 v[14:17], v[114:117], v[208:211], v[14:17]
	v_mfma_f32_16x16x32_bf16 v[10:13], v[122:125], v[208:211], v[10:13]
	v_mfma_f32_16x16x32_bf16 v[62:65], v[118:121], v[188:191], v[62:65]
	v_mfma_f32_16x16x32_bf16 v[58:61], v[134:137], v[188:191], v[58:61]
	v_mfma_f32_16x16x32_bf16 v[46:49], v[118:121], v[196:199], v[46:49]
	v_mfma_f32_16x16x32_bf16 v[42:45], v[134:137], v[196:199], v[42:45]
	v_mfma_f32_16x16x32_bf16 v[30:33], v[118:121], v[204:207], v[30:33]
	v_mfma_f32_16x16x32_bf16 v[26:29], v[134:137], v[204:207], v[26:29]
	v_mfma_f32_16x16x32_bf16 v[14:17], v[118:121], v[212:215], v[14:17]
	v_mfma_f32_16x16x32_bf16 v[10:13], v[134:137], v[212:215], v[10:13]
	v_mfma_f32_16x16x32_bf16 v[54:57], v[146:149], v[180:183], v[54:57]
	v_mfma_f32_16x16x32_bf16 v[50:53], v[166:169], v[180:183], v[50:53]
	v_mfma_f32_16x16x32_bf16 v[38:41], v[146:149], v[192:195], v[38:41]
	v_mfma_f32_16x16x32_bf16 v[34:37], v[166:169], v[192:195], v[34:37]
	v_mfma_f32_16x16x32_bf16 v[22:25], v[146:149], v[200:203], v[22:25]
	v_mfma_f32_16x16x32_bf16 v[18:21], v[166:169], v[200:203], v[18:21]
	v_mfma_f32_16x16x32_bf16 v[6:9], v[146:149], v[208:211], v[6:9]
	v_mfma_f32_16x16x32_bf16 v[2:5], v[166:169], v[208:211], v[2:5]
	v_mfma_f32_16x16x32_bf16 v[54:57], v[150:153], v[188:191], v[54:57]
	v_mfma_f32_16x16x32_bf16 v[50:53], v[170:173], v[188:191], v[50:53]
	v_mfma_f32_16x16x32_bf16 v[38:41], v[150:153], v[196:199], v[38:41]
	v_mfma_f32_16x16x32_bf16 v[34:37], v[170:173], v[196:199], v[34:37]
	v_mfma_f32_16x16x32_bf16 v[22:25], v[150:153], v[204:207], v[22:25]
	v_mfma_f32_16x16x32_bf16 v[18:21], v[170:173], v[204:207], v[18:21]
	v_mfma_f32_16x16x32_bf16 v[6:9], v[150:153], v[212:215], v[6:9]
	v_mfma_f32_16x16x32_bf16 v[2:5], v[170:173], v[212:215], v[2:5]
	s_barrier
	s_add_i32 s50, s50, 2
	s_add_u32 s33, s33, 0x100
	s_addc_u32 s49, s49, 0
	s_cmp_gt_u32 s50, 41
	s_mov_b64 s[22:23], s[8:9]
	s_cbranch_scc0 .LBB0_1360
	s_and_b64 vcc, exec, s[14:15]
	s_cbranch_vccz .LBB0_1363
	s_barrier
